# fused residual stages: acc*rstd and x += acc*g as packed f32 ops (192+192 pairs)
# speedup vs baseline: 1.0144x; 1.0020x over previous
.LBB0_852:
	s_or_b64 exec, exec, s[0:1]
	s_waitcnt lgkmcnt(0)
	s_barrier
	s_and_b32 s98, s2, 7
	s_lshl_b32 s98, s98, 3
	s_bfe_u32 s99, s2, 0x30003
	s_or_b32 s98, s98, s99
	s_lshr_b32 s99, s2, 6
	v_and_b32_e32 v172, 0xff, v136
	v_lshrrev_b32_e32 v173, 8, v136
	v_mul_u32_u24_e32 v173, 0x84000, v173
	v_lshl_add_u32 v172, v172, 2, v173
	s_lshl_b32 s24, s98, 10
	s_add_u32 s18, s44, s24
	s_addc_u32 s19, s45, 0
	global_load_dword v164, v172, s[18:19]
	s_add_u32 s18, s18, 0x10800
	s_addc_u32 s19, s19, 0
	global_load_dword v165, v172, s[18:19]
	s_add_u32 s18, s18, 0x10800
	s_addc_u32 s19, s19, 0
	global_load_dword v166, v172, s[18:19]
	s_add_u32 s18, s18, 0x10800
	s_addc_u32 s19, s19, 0
	global_load_dword v167, v172, s[18:19]
	s_add_u32 s18, s18, 0x10800
	s_addc_u32 s19, s19, 0
	global_load_dword v168, v172, s[18:19]
	s_add_u32 s18, s18, 0x10800
	s_addc_u32 s19, s19, 0
	global_load_dword v169, v172, s[18:19]
	s_add_u32 s18, s18, 0x10800
	s_addc_u32 s19, s19, 0
	global_load_dword v170, v172, s[18:19]
	s_add_u32 s18, s18, 0x10800
	s_addc_u32 s19, s19, 0
	global_load_dword v171, v172, s[18:19]
	v_lshrrev_b32_e32 v141, 8, v136
	v_and_b32_e32 v142, 15, v136
	v_lshl_add_u32 v141, v141, 6, v142
	v_bfe_u32 v144, v136, 6, 2
	v_bfe_u32 v145, v136, 4, 2
	v_lshlrev_b32_e32 v144, 5, v144
	v_lshl_add_u32 v144, v145, 3, v144
	s_lshl_b32 s24, s99, 8
	v_add_u32_e32 v144, s24, v144
	s_lshl_b32 s25, s98, 8
	v_add_u32_e32 v145, s25, v141
	v_lshl_add_u32 v146, v145, 10, v144
	v_lshlrev_b32_e32 v140, 1, v146
	v_lshlrev_b32_e32 v147, 2, v144
	v_readlane_b32 s18, v253, 3
	v_readlane_b32 s19, v253, 4
	v_readlane_b32 s20, v253, 53
	v_readlane_b32 s21, v253, 54
	s_nop 4
	s_add_u32 s18, s18, 0x1000
	s_addc_u32 s19, s19, 0
	global_load_dwordx4 v[148:151], v147, s[18:19]
	global_load_dwordx4 v[152:155], v147, s[18:19] offset:16
	global_load_dwordx4 v[156:159], v147, s[18:19] offset:512
	global_load_dwordx4 v[160:163], v147, s[18:19] offset:528
	s_add_u32 s22, s20, 0x0
	s_addc_u32 s23, s21, 0
	global_load_dwordx4 v[188:191], v140, s[22:23] nt
	global_load_dwordx4 v[192:195], v140, s[22:23] offset:256 nt
	s_add_u32 s22, s20, 0x8000
	s_addc_u32 s23, s21, 0
	global_load_dwordx4 v[196:199], v140, s[22:23] nt
	global_load_dwordx4 v[200:203], v140, s[22:23] offset:256 nt
	s_add_u32 s22, s20, 0x10000
	s_addc_u32 s23, s21, 0
	global_load_dwordx4 v[204:207], v140, s[22:23] nt
	global_load_dwordx4 v[208:211], v140, s[22:23] offset:256 nt
	s_add_u32 s22, s20, 0x18000
	s_addc_u32 s23, s21, 0
	global_load_dwordx4 v[212:215], v140, s[22:23] nt
	global_load_dwordx4 v[216:219], v140, s[22:23] offset:256 nt
	s_add_u32 s22, s20, 0x40000
	s_addc_u32 s23, s21, 0
	global_load_dwordx4 v[220:223], v140, s[22:23] nt
	global_load_dwordx4 v[224:227], v140, s[22:23] offset:256 nt
	s_add_u32 s22, s20, 0x48000
	s_addc_u32 s23, s21, 0
	global_load_dwordx4 v[228:231], v140, s[22:23] nt
	global_load_dwordx4 v[232:235], v140, s[22:23] offset:256 nt
	s_add_u32 s22, s20, 0x50000
	s_addc_u32 s23, s21, 0
	global_load_dwordx4 v[236:239], v140, s[22:23] nt
	global_load_dwordx4 v[240:243], v140, s[22:23] offset:256 nt
	s_add_u32 s22, s20, 0x58000
	s_addc_u32 s23, s21, 0
	global_load_dwordx4 v[244:247], v140, s[22:23] nt
	global_load_dwordx4 v[248:251], v140, s[22:23] offset:256 nt
	s_waitcnt vmcnt(20)
	v_add_f32_e32 v164, v164, v165
	v_add_f32_e32 v164, v164, v166
	v_add_f32_e32 v164, v164, v167
	v_add_f32_e32 v164, v164, v168
	v_add_f32_e32 v164, v164, v169
	v_add_f32_e32 v164, v164, v170
	v_add_f32_e32 v164, v164, v171
	v_lshlrev_b32_e32 v173, 2, v136
	ds_write_b32 v173, v164
	s_waitcnt lgkmcnt(0)
	s_barrier
	v_lshlrev_b32_e32 v142, 2, v141
	ds_read_b32 v128, v142 offset:0
	ds_read_b32 v174, v142 offset:1024
	ds_read_b32 v129, v142 offset:64
	ds_read_b32 v175, v142 offset:1088
	ds_read_b32 v130, v142 offset:128
	ds_read_b32 v176, v142 offset:1152
	ds_read_b32 v131, v142 offset:192
	ds_read_b32 v177, v142 offset:1216
	ds_read_b32 v132, v142 offset:512
	ds_read_b32 v178, v142 offset:1536
	ds_read_b32 v133, v142 offset:576
	ds_read_b32 v179, v142 offset:1600
	ds_read_b32 v134, v142 offset:640
	ds_read_b32 v180, v142 offset:1664
	ds_read_b32 v135, v142 offset:704
	ds_read_b32 v181, v142 offset:1728
	s_waitcnt lgkmcnt(0)
	s_mov_b32 s101, 0x3a800000
	v_mov_b32_e32 v143, 0x358637bd
	v_add_f32_e32 v128, v128, v174
	v_add_f32_e32 v129, v129, v175
	v_add_f32_e32 v130, v130, v176
	v_add_f32_e32 v131, v131, v177
	v_add_f32_e32 v132, v132, v178
	v_add_f32_e32 v133, v133, v179
	v_add_f32_e32 v134, v134, v180
	v_add_f32_e32 v135, v135, v181
	v_fma_f32 v128, v128, s101, v143
	v_fma_f32 v129, v129, s101, v143
	v_fma_f32 v130, v130, s101, v143
	v_fma_f32 v131, v131, s101, v143
	v_fma_f32 v132, v132, s101, v143
	v_fma_f32 v133, v133, s101, v143
	v_fma_f32 v134, v134, s101, v143
	v_fma_f32 v135, v135, s101, v143
	v_rsq_f32_e32 v128, v128
	v_rsq_f32_e32 v129, v129
	v_rsq_f32_e32 v130, v130
	v_rsq_f32_e32 v131, v131
	v_rsq_f32_e32 v132, v132
	v_rsq_f32_e32 v133, v133
	v_rsq_f32_e32 v134, v134
	v_rsq_f32_e32 v135, v135
	s_waitcnt vmcnt(0)
	s_add_u32 s22, s60, 0x0
	s_addc_u32 s23, s61, 0
	v_lshlrev_b32_e32 v164, 16, v188
	v_and_b32_e32 v165, 0xffff0000, v188
	v_lshlrev_b32_e32 v166, 16, v189
	v_and_b32_e32 v167, 0xffff0000, v189
	v_lshlrev_b32_e32 v168, 16, v190
	v_and_b32_e32 v169, 0xffff0000, v190
	v_lshlrev_b32_e32 v170, 16, v191
	v_and_b32_e32 v171, 0xffff0000, v191
	v_pk_mul_f32 v[124:125], v[124:125], v[128:129] op_sel_hi:[1,0]
	v_pk_mul_f32 v[126:127], v[126:127], v[128:129] op_sel_hi:[1,0]
	v_pk_mul_f32 v[112:113], v[112:113], v[128:129] op_sel_hi:[1,0]
	v_pk_mul_f32 v[114:115], v[114:115], v[128:129] op_sel_hi:[1,0]
	v_pk_fma_f32 v[164:165], v[124:125], v[148:149], v[164:165]
	v_pk_fma_f32 v[166:167], v[126:127], v[150:151], v[166:167]
	v_pk_fma_f32 v[168:169], v[112:113], v[152:153], v[168:169]
	v_pk_fma_f32 v[170:171], v[114:115], v[154:155], v[170:171]
	v_mul_f32_e32 v138, v164, v164
	v_fmac_f32_e32 v138, v165, v165
	v_fmac_f32_e32 v138, v166, v166
	v_fmac_f32_e32 v138, v167, v167
	v_fmac_f32_e32 v138, v168, v168
	v_fmac_f32_e32 v138, v169, v169
	v_fmac_f32_e32 v138, v170, v170
	v_fmac_f32_e32 v138, v171, v171
	v_cvt_pk_bf16_f32 v180, v164, v165
	v_cvt_pk_bf16_f32 v181, v166, v167
	v_cvt_pk_bf16_f32 v182, v168, v169
	v_cvt_pk_bf16_f32 v183, v170, v171
	global_store_dwordx4 v140, v[180:183], s[22:23]
	v_lshlrev_b32_e32 v172, 16, v192
	v_and_b32_e32 v173, 0xffff0000, v192
	v_lshlrev_b32_e32 v174, 16, v193
	v_and_b32_e32 v175, 0xffff0000, v193
	v_lshlrev_b32_e32 v176, 16, v194
	v_and_b32_e32 v177, 0xffff0000, v194
	v_lshlrev_b32_e32 v178, 16, v195
	v_and_b32_e32 v179, 0xffff0000, v195
	v_pk_mul_f32 v[120:121], v[120:121], v[128:129] op_sel_hi:[1,0]
	v_pk_mul_f32 v[122:123], v[122:123], v[128:129] op_sel_hi:[1,0]
	v_pk_mul_f32 v[116:117], v[116:117], v[128:129] op_sel_hi:[1,0]
	v_pk_mul_f32 v[118:119], v[118:119], v[128:129] op_sel_hi:[1,0]
	v_pk_fma_f32 v[172:173], v[120:121], v[156:157], v[172:173]
	v_pk_fma_f32 v[174:175], v[122:123], v[158:159], v[174:175]
	v_pk_fma_f32 v[176:177], v[116:117], v[160:161], v[176:177]
	v_pk_fma_f32 v[178:179], v[118:119], v[162:163], v[178:179]
	v_fmac_f32_e32 v138, v172, v172
	v_fmac_f32_e32 v138, v173, v173
	v_fmac_f32_e32 v138, v174, v174
	v_fmac_f32_e32 v138, v175, v175
	v_fmac_f32_e32 v138, v176, v176
	v_fmac_f32_e32 v138, v177, v177
	v_fmac_f32_e32 v138, v178, v178
	v_fmac_f32_e32 v138, v179, v179
	v_cvt_pk_bf16_f32 v184, v172, v173
	v_cvt_pk_bf16_f32 v185, v174, v175
	v_cvt_pk_bf16_f32 v186, v176, v177
	v_cvt_pk_bf16_f32 v187, v178, v179
	global_store_dwordx4 v140, v[184:187], s[22:23] offset:256
	s_add_u32 s22, s60, 0x8000
	s_addc_u32 s23, s61, 0
	v_lshlrev_b32_e32 v164, 16, v196
	v_and_b32_e32 v165, 0xffff0000, v196
	v_lshlrev_b32_e32 v166, 16, v197
	v_and_b32_e32 v167, 0xffff0000, v197
	v_lshlrev_b32_e32 v168, 16, v198
	v_and_b32_e32 v169, 0xffff0000, v198
	v_lshlrev_b32_e32 v170, 16, v199
	v_and_b32_e32 v171, 0xffff0000, v199
	v_pk_mul_f32 v[108:109], v[108:109], v[128:129] op_sel:[0,1] op_sel_hi:[1,1]
	v_pk_mul_f32 v[110:111], v[110:111], v[128:129] op_sel:[0,1] op_sel_hi:[1,1]
	v_pk_mul_f32 v[96:97], v[96:97], v[128:129] op_sel:[0,1] op_sel_hi:[1,1]
	v_pk_mul_f32 v[98:99], v[98:99], v[128:129] op_sel:[0,1] op_sel_hi:[1,1]
	v_pk_fma_f32 v[164:165], v[108:109], v[148:149], v[164:165]
	v_pk_fma_f32 v[166:167], v[110:111], v[150:151], v[166:167]
	v_pk_fma_f32 v[168:169], v[96:97], v[152:153], v[168:169]
	v_pk_fma_f32 v[170:171], v[98:99], v[154:155], v[170:171]
	v_mul_f32_e32 v139, v164, v164
	v_fmac_f32_e32 v139, v165, v165
	v_fmac_f32_e32 v139, v166, v166
	v_fmac_f32_e32 v139, v167, v167
	v_fmac_f32_e32 v139, v168, v168
	v_fmac_f32_e32 v139, v169, v169
	v_fmac_f32_e32 v139, v170, v170
	v_fmac_f32_e32 v139, v171, v171
	v_cvt_pk_bf16_f32 v180, v164, v165
	v_cvt_pk_bf16_f32 v181, v166, v167
	v_cvt_pk_bf16_f32 v182, v168, v169
	v_cvt_pk_bf16_f32 v183, v170, v171
	global_store_dwordx4 v140, v[180:183], s[22:23]
	v_lshlrev_b32_e32 v172, 16, v200
	v_and_b32_e32 v173, 0xffff0000, v200
	v_lshlrev_b32_e32 v174, 16, v201
	v_and_b32_e32 v175, 0xffff0000, v201
	v_lshlrev_b32_e32 v176, 16, v202
	v_and_b32_e32 v177, 0xffff0000, v202
	v_lshlrev_b32_e32 v178, 16, v203
	v_and_b32_e32 v179, 0xffff0000, v203
	v_pk_mul_f32 v[100:101], v[100:101], v[128:129] op_sel:[0,1] op_sel_hi:[1,1]
	v_pk_mul_f32 v[102:103], v[102:103], v[128:129] op_sel:[0,1] op_sel_hi:[1,1]
	v_pk_mul_f32 v[104:105], v[104:105], v[128:129] op_sel:[0,1] op_sel_hi:[1,1]
	v_pk_mul_f32 v[106:107], v[106:107], v[128:129] op_sel:[0,1] op_sel_hi:[1,1]
	v_pk_fma_f32 v[172:173], v[100:101], v[156:157], v[172:173]
	v_pk_fma_f32 v[174:175], v[102:103], v[158:159], v[174:175]
	v_pk_fma_f32 v[176:177], v[104:105], v[160:161], v[176:177]
	v_pk_fma_f32 v[178:179], v[106:107], v[162:163], v[178:179]
	v_fmac_f32_e32 v139, v172, v172
	v_fmac_f32_e32 v139, v173, v173
	v_fmac_f32_e32 v139, v174, v174
	v_fmac_f32_e32 v139, v175, v175
	v_fmac_f32_e32 v139, v176, v176
	v_fmac_f32_e32 v139, v177, v177
	v_fmac_f32_e32 v139, v178, v178
	v_fmac_f32_e32 v139, v179, v179
	v_cvt_pk_bf16_f32 v184, v172, v173
	v_cvt_pk_bf16_f32 v185, v174, v175
	v_cvt_pk_bf16_f32 v186, v176, v177
	v_cvt_pk_bf16_f32 v187, v178, v179
	global_store_dwordx4 v140, v[184:187], s[22:23] offset:256
	s_add_u32 s22, s60, 0x10000
	s_addc_u32 s23, s61, 0
	v_lshlrev_b32_e32 v164, 16, v204
	v_and_b32_e32 v165, 0xffff0000, v204
	v_lshlrev_b32_e32 v166, 16, v205
	v_and_b32_e32 v167, 0xffff0000, v205
	v_lshlrev_b32_e32 v168, 16, v206
	v_and_b32_e32 v169, 0xffff0000, v206
	v_lshlrev_b32_e32 v170, 16, v207
	v_and_b32_e32 v171, 0xffff0000, v207
	v_pk_mul_f32 v[92:93], v[92:93], v[130:131] op_sel_hi:[1,0]
	v_pk_mul_f32 v[94:95], v[94:95], v[130:131] op_sel_hi:[1,0]
	v_pk_mul_f32 v[80:81], v[80:81], v[130:131] op_sel_hi:[1,0]
	v_pk_mul_f32 v[82:83], v[82:83], v[130:131] op_sel_hi:[1,0]
	v_pk_fma_f32 v[164:165], v[92:93], v[148:149], v[164:165]
	v_pk_fma_f32 v[166:167], v[94:95], v[150:151], v[166:167]
	v_pk_fma_f32 v[168:169], v[80:81], v[152:153], v[168:169]
	v_pk_fma_f32 v[170:171], v[82:83], v[154:155], v[170:171]
	v_mul_f32_e32 v141, v164, v164
	v_fmac_f32_e32 v141, v165, v165
	v_fmac_f32_e32 v141, v166, v166
	v_fmac_f32_e32 v141, v167, v167
	v_fmac_f32_e32 v141, v168, v168
	v_fmac_f32_e32 v141, v169, v169
	v_fmac_f32_e32 v141, v170, v170
	v_fmac_f32_e32 v141, v171, v171
	v_cvt_pk_bf16_f32 v180, v164, v165
	v_cvt_pk_bf16_f32 v181, v166, v167
	v_cvt_pk_bf16_f32 v182, v168, v169
	v_cvt_pk_bf16_f32 v183, v170, v171
	global_store_dwordx4 v140, v[180:183], s[22:23]
	v_lshlrev_b32_e32 v172, 16, v208
	v_and_b32_e32 v173, 0xffff0000, v208
	v_lshlrev_b32_e32 v174, 16, v209
	v_and_b32_e32 v175, 0xffff0000, v209
	v_lshlrev_b32_e32 v176, 16, v210
	v_and_b32_e32 v177, 0xffff0000, v210
	v_lshlrev_b32_e32 v178, 16, v211
	v_and_b32_e32 v179, 0xffff0000, v211
	v_pk_mul_f32 v[84:85], v[84:85], v[130:131] op_sel_hi:[1,0]
	v_pk_mul_f32 v[86:87], v[86:87], v[130:131] op_sel_hi:[1,0]
	v_pk_mul_f32 v[88:89], v[88:89], v[130:131] op_sel_hi:[1,0]
	v_pk_mul_f32 v[90:91], v[90:91], v[130:131] op_sel_hi:[1,0]
	v_pk_fma_f32 v[172:173], v[84:85], v[156:157], v[172:173]
	v_pk_fma_f32 v[174:175], v[86:87], v[158:159], v[174:175]
	v_pk_fma_f32 v[176:177], v[88:89], v[160:161], v[176:177]
	v_pk_fma_f32 v[178:179], v[90:91], v[162:163], v[178:179]
	v_fmac_f32_e32 v141, v172, v172
	v_fmac_f32_e32 v141, v173, v173
	v_fmac_f32_e32 v141, v174, v174
	v_fmac_f32_e32 v141, v175, v175
	v_fmac_f32_e32 v141, v176, v176
	v_fmac_f32_e32 v141, v177, v177
	v_fmac_f32_e32 v141, v178, v178
	v_fmac_f32_e32 v141, v179, v179
	v_cvt_pk_bf16_f32 v184, v172, v173
	v_cvt_pk_bf16_f32 v185, v174, v175
	v_cvt_pk_bf16_f32 v186, v176, v177
	v_cvt_pk_bf16_f32 v187, v178, v179
	global_store_dwordx4 v140, v[184:187], s[22:23] offset:256
	s_add_u32 s22, s60, 0x18000
	s_addc_u32 s23, s61, 0
	v_lshlrev_b32_e32 v164, 16, v212
	v_and_b32_e32 v165, 0xffff0000, v212
	v_lshlrev_b32_e32 v166, 16, v213
	v_and_b32_e32 v167, 0xffff0000, v213
	v_lshlrev_b32_e32 v168, 16, v214
	v_and_b32_e32 v169, 0xffff0000, v214
	v_lshlrev_b32_e32 v170, 16, v215
	v_and_b32_e32 v171, 0xffff0000, v215
	v_pk_mul_f32 v[76:77], v[76:77], v[130:131] op_sel:[0,1] op_sel_hi:[1,1]
	v_pk_mul_f32 v[78:79], v[78:79], v[130:131] op_sel:[0,1] op_sel_hi:[1,1]
	v_pk_mul_f32 v[64:65], v[64:65], v[130:131] op_sel:[0,1] op_sel_hi:[1,1]
	v_pk_mul_f32 v[66:67], v[66:67], v[130:131] op_sel:[0,1] op_sel_hi:[1,1]
	v_pk_fma_f32 v[164:165], v[76:77], v[148:149], v[164:165]
	v_pk_fma_f32 v[166:167], v[78:79], v[150:151], v[166:167]
	v_pk_fma_f32 v[168:169], v[64:65], v[152:153], v[168:169]
	v_pk_fma_f32 v[170:171], v[66:67], v[154:155], v[170:171]
	v_mul_f32_e32 v142, v164, v164
	v_fmac_f32_e32 v142, v165, v165
	v_fmac_f32_e32 v142, v166, v166
	v_fmac_f32_e32 v142, v167, v167
	v_fmac_f32_e32 v142, v168, v168
	v_fmac_f32_e32 v142, v169, v169
	v_fmac_f32_e32 v142, v170, v170
	v_fmac_f32_e32 v142, v171, v171
	v_cvt_pk_bf16_f32 v180, v164, v165
	v_cvt_pk_bf16_f32 v181, v166, v167
	v_cvt_pk_bf16_f32 v182, v168, v169
	v_cvt_pk_bf16_f32 v183, v170, v171
	global_store_dwordx4 v140, v[180:183], s[22:23]
	v_lshlrev_b32_e32 v172, 16, v216
	v_and_b32_e32 v173, 0xffff0000, v216
	v_lshlrev_b32_e32 v174, 16, v217
	v_and_b32_e32 v175, 0xffff0000, v217
	v_lshlrev_b32_e32 v176, 16, v218
	v_and_b32_e32 v177, 0xffff0000, v218
	v_lshlrev_b32_e32 v178, 16, v219
	v_and_b32_e32 v179, 0xffff0000, v219
	v_pk_mul_f32 v[68:69], v[68:69], v[130:131] op_sel:[0,1] op_sel_hi:[1,1]
	v_pk_mul_f32 v[70:71], v[70:71], v[130:131] op_sel:[0,1] op_sel_hi:[1,1]
	v_pk_mul_f32 v[72:73], v[72:73], v[130:131] op_sel:[0,1] op_sel_hi:[1,1]
	v_pk_mul_f32 v[74:75], v[74:75], v[130:131] op_sel:[0,1] op_sel_hi:[1,1]
	v_pk_fma_f32 v[172:173], v[68:69], v[156:157], v[172:173]
	v_pk_fma_f32 v[174:175], v[70:71], v[158:159], v[174:175]
	v_pk_fma_f32 v[176:177], v[72:73], v[160:161], v[176:177]
	v_pk_fma_f32 v[178:179], v[74:75], v[162:163], v[178:179]
	v_fmac_f32_e32 v142, v172, v172
	v_fmac_f32_e32 v142, v173, v173
	v_fmac_f32_e32 v142, v174, v174
	v_fmac_f32_e32 v142, v175, v175
	v_fmac_f32_e32 v142, v176, v176
	v_fmac_f32_e32 v142, v177, v177
	v_fmac_f32_e32 v142, v178, v178
	v_fmac_f32_e32 v142, v179, v179
	v_cvt_pk_bf16_f32 v184, v172, v173
	v_cvt_pk_bf16_f32 v185, v174, v175
	v_cvt_pk_bf16_f32 v186, v176, v177
	v_cvt_pk_bf16_f32 v187, v178, v179
	global_store_dwordx4 v140, v[184:187], s[22:23] offset:256
	s_add_u32 s22, s60, 0x40000
	s_addc_u32 s23, s61, 0
	v_lshlrev_b32_e32 v164, 16, v220
	v_and_b32_e32 v165, 0xffff0000, v220
	v_lshlrev_b32_e32 v166, 16, v221
	v_and_b32_e32 v167, 0xffff0000, v221
	v_lshlrev_b32_e32 v168, 16, v222
	v_and_b32_e32 v169, 0xffff0000, v222
	v_lshlrev_b32_e32 v170, 16, v223
	v_and_b32_e32 v171, 0xffff0000, v223
	v_pk_mul_f32 v[60:61], v[60:61], v[132:133] op_sel_hi:[1,0]
	v_pk_mul_f32 v[62:63], v[62:63], v[132:133] op_sel_hi:[1,0]
	v_pk_mul_f32 v[48:49], v[48:49], v[132:133] op_sel_hi:[1,0]
	v_pk_mul_f32 v[50:51], v[50:51], v[132:133] op_sel_hi:[1,0]
	v_pk_fma_f32 v[164:165], v[60:61], v[148:149], v[164:165]
	v_pk_fma_f32 v[166:167], v[62:63], v[150:151], v[166:167]
	v_pk_fma_f32 v[168:169], v[48:49], v[152:153], v[168:169]
	v_pk_fma_f32 v[170:171], v[50:51], v[154:155], v[170:171]
	v_mul_f32_e32 v143, v164, v164
	v_fmac_f32_e32 v143, v165, v165
	v_fmac_f32_e32 v143, v166, v166
	v_fmac_f32_e32 v143, v167, v167
	v_fmac_f32_e32 v143, v168, v168
	v_fmac_f32_e32 v143, v169, v169
	v_fmac_f32_e32 v143, v170, v170
	v_fmac_f32_e32 v143, v171, v171
	v_cvt_pk_bf16_f32 v180, v164, v165
	v_cvt_pk_bf16_f32 v181, v166, v167
	v_cvt_pk_bf16_f32 v182, v168, v169
	v_cvt_pk_bf16_f32 v183, v170, v171
	global_store_dwordx4 v140, v[180:183], s[22:23]
	v_lshlrev_b32_e32 v172, 16, v224
	v_and_b32_e32 v173, 0xffff0000, v224
	v_lshlrev_b32_e32 v174, 16, v225
	v_and_b32_e32 v175, 0xffff0000, v225
	v_lshlrev_b32_e32 v176, 16, v226
	v_and_b32_e32 v177, 0xffff0000, v226
	v_lshlrev_b32_e32 v178, 16, v227
	v_and_b32_e32 v179, 0xffff0000, v227
	v_pk_mul_f32 v[52:53], v[52:53], v[132:133] op_sel_hi:[1,0]
	v_pk_mul_f32 v[54:55], v[54:55], v[132:133] op_sel_hi:[1,0]
	v_pk_mul_f32 v[56:57], v[56:57], v[132:133] op_sel_hi:[1,0]
	v_pk_mul_f32 v[58:59], v[58:59], v[132:133] op_sel_hi:[1,0]
	v_pk_fma_f32 v[172:173], v[52:53], v[156:157], v[172:173]
	v_pk_fma_f32 v[174:175], v[54:55], v[158:159], v[174:175]
	v_pk_fma_f32 v[176:177], v[56:57], v[160:161], v[176:177]
	v_pk_fma_f32 v[178:179], v[58:59], v[162:163], v[178:179]
	v_fmac_f32_e32 v143, v172, v172
	v_fmac_f32_e32 v143, v173, v173
	v_fmac_f32_e32 v143, v174, v174
	v_fmac_f32_e32 v143, v175, v175
	v_fmac_f32_e32 v143, v176, v176
	v_fmac_f32_e32 v143, v177, v177
	v_fmac_f32_e32 v143, v178, v178
	v_fmac_f32_e32 v143, v179, v179
	v_cvt_pk_bf16_f32 v184, v172, v173
	v_cvt_pk_bf16_f32 v185, v174, v175
	v_cvt_pk_bf16_f32 v186, v176, v177
	v_cvt_pk_bf16_f32 v187, v178, v179
	global_store_dwordx4 v140, v[184:187], s[22:23] offset:256
	s_add_u32 s22, s60, 0x48000
	s_addc_u32 s23, s61, 0
	v_lshlrev_b32_e32 v164, 16, v228
	v_and_b32_e32 v165, 0xffff0000, v228
	v_lshlrev_b32_e32 v166, 16, v229
	v_and_b32_e32 v167, 0xffff0000, v229
	v_lshlrev_b32_e32 v168, 16, v230
	v_and_b32_e32 v169, 0xffff0000, v230
	v_lshlrev_b32_e32 v170, 16, v231
	v_and_b32_e32 v171, 0xffff0000, v231
	v_pk_mul_f32 v[44:45], v[44:45], v[132:133] op_sel:[0,1] op_sel_hi:[1,1]
	v_pk_mul_f32 v[46:47], v[46:47], v[132:133] op_sel:[0,1] op_sel_hi:[1,1]
	v_pk_mul_f32 v[32:33], v[32:33], v[132:133] op_sel:[0,1] op_sel_hi:[1,1]
	v_pk_mul_f32 v[34:35], v[34:35], v[132:133] op_sel:[0,1] op_sel_hi:[1,1]
	v_pk_fma_f32 v[164:165], v[44:45], v[148:149], v[164:165]
	v_pk_fma_f32 v[166:167], v[46:47], v[150:151], v[166:167]
	v_pk_fma_f32 v[168:169], v[32:33], v[152:153], v[168:169]
	v_pk_fma_f32 v[170:171], v[34:35], v[154:155], v[170:171]
	v_mul_f32_e32 v144, v164, v164
	v_fmac_f32_e32 v144, v165, v165
	v_fmac_f32_e32 v144, v166, v166
	v_fmac_f32_e32 v144, v167, v167
	v_fmac_f32_e32 v144, v168, v168
	v_fmac_f32_e32 v144, v169, v169
	v_fmac_f32_e32 v144, v170, v170
	v_fmac_f32_e32 v144, v171, v171
	v_cvt_pk_bf16_f32 v180, v164, v165
	v_cvt_pk_bf16_f32 v181, v166, v167
	v_cvt_pk_bf16_f32 v182, v168, v169
	v_cvt_pk_bf16_f32 v183, v170, v171
	global_store_dwordx4 v140, v[180:183], s[22:23]
	v_lshlrev_b32_e32 v172, 16, v232
	v_and_b32_e32 v173, 0xffff0000, v232
	v_lshlrev_b32_e32 v174, 16, v233
	v_and_b32_e32 v175, 0xffff0000, v233
	v_lshlrev_b32_e32 v176, 16, v234
	v_and_b32_e32 v177, 0xffff0000, v234
	v_lshlrev_b32_e32 v178, 16, v235
	v_and_b32_e32 v179, 0xffff0000, v235
	v_pk_mul_f32 v[36:37], v[36:37], v[132:133] op_sel:[0,1] op_sel_hi:[1,1]
	v_pk_mul_f32 v[38:39], v[38:39], v[132:133] op_sel:[0,1] op_sel_hi:[1,1]
	v_pk_mul_f32 v[40:41], v[40:41], v[132:133] op_sel:[0,1] op_sel_hi:[1,1]
	v_pk_mul_f32 v[42:43], v[42:43], v[132:133] op_sel:[0,1] op_sel_hi:[1,1]
	v_pk_fma_f32 v[172:173], v[36:37], v[156:157], v[172:173]
	v_pk_fma_f32 v[174:175], v[38:39], v[158:159], v[174:175]
	v_pk_fma_f32 v[176:177], v[40:41], v[160:161], v[176:177]
	v_pk_fma_f32 v[178:179], v[42:43], v[162:163], v[178:179]
	v_fmac_f32_e32 v144, v172, v172
	v_fmac_f32_e32 v144, v173, v173
	v_fmac_f32_e32 v144, v174, v174
	v_fmac_f32_e32 v144, v175, v175
	v_fmac_f32_e32 v144, v176, v176
	v_fmac_f32_e32 v144, v177, v177
	v_fmac_f32_e32 v144, v178, v178
	v_fmac_f32_e32 v144, v179, v179
	v_cvt_pk_bf16_f32 v184, v172, v173
	v_cvt_pk_bf16_f32 v185, v174, v175
	v_cvt_pk_bf16_f32 v186, v176, v177
	v_cvt_pk_bf16_f32 v187, v178, v179
	global_store_dwordx4 v140, v[184:187], s[22:23] offset:256
	s_add_u32 s22, s60, 0x50000
	s_addc_u32 s23, s61, 0
	v_lshlrev_b32_e32 v164, 16, v236
	v_and_b32_e32 v165, 0xffff0000, v236
	v_lshlrev_b32_e32 v166, 16, v237
	v_and_b32_e32 v167, 0xffff0000, v237
	v_lshlrev_b32_e32 v168, 16, v238
	v_and_b32_e32 v169, 0xffff0000, v238
	v_lshlrev_b32_e32 v170, 16, v239
	v_and_b32_e32 v171, 0xffff0000, v239
	v_pk_mul_f32 v[28:29], v[28:29], v[134:135] op_sel_hi:[1,0]
	v_pk_mul_f32 v[30:31], v[30:31], v[134:135] op_sel_hi:[1,0]
	v_pk_mul_f32 v[16:17], v[16:17], v[134:135] op_sel_hi:[1,0]
	v_pk_mul_f32 v[18:19], v[18:19], v[134:135] op_sel_hi:[1,0]
	v_pk_fma_f32 v[164:165], v[28:29], v[148:149], v[164:165]
	v_pk_fma_f32 v[166:167], v[30:31], v[150:151], v[166:167]
	v_pk_fma_f32 v[168:169], v[16:17], v[152:153], v[168:169]
	v_pk_fma_f32 v[170:171], v[18:19], v[154:155], v[170:171]
	v_mul_f32_e32 v145, v164, v164
	v_fmac_f32_e32 v145, v165, v165
	v_fmac_f32_e32 v145, v166, v166
	v_fmac_f32_e32 v145, v167, v167
	v_fmac_f32_e32 v145, v168, v168
	v_fmac_f32_e32 v145, v169, v169
	v_fmac_f32_e32 v145, v170, v170
	v_fmac_f32_e32 v145, v171, v171
	v_cvt_pk_bf16_f32 v180, v164, v165
	v_cvt_pk_bf16_f32 v181, v166, v167
	v_cvt_pk_bf16_f32 v182, v168, v169
	v_cvt_pk_bf16_f32 v183, v170, v171
	global_store_dwordx4 v140, v[180:183], s[22:23]
	v_lshlrev_b32_e32 v172, 16, v240
	v_and_b32_e32 v173, 0xffff0000, v240
	v_lshlrev_b32_e32 v174, 16, v241
	v_and_b32_e32 v175, 0xffff0000, v241
	v_lshlrev_b32_e32 v176, 16, v242
	v_and_b32_e32 v177, 0xffff0000, v242
	v_lshlrev_b32_e32 v178, 16, v243
	v_and_b32_e32 v179, 0xffff0000, v243
	v_pk_mul_f32 v[20:21], v[20:21], v[134:135] op_sel_hi:[1,0]
	v_pk_mul_f32 v[22:23], v[22:23], v[134:135] op_sel_hi:[1,0]
	v_pk_mul_f32 v[24:25], v[24:25], v[134:135] op_sel_hi:[1,0]
	v_pk_mul_f32 v[26:27], v[26:27], v[134:135] op_sel_hi:[1,0]
	v_pk_fma_f32 v[172:173], v[20:21], v[156:157], v[172:173]
	v_pk_fma_f32 v[174:175], v[22:23], v[158:159], v[174:175]
	v_pk_fma_f32 v[176:177], v[24:25], v[160:161], v[176:177]
	v_pk_fma_f32 v[178:179], v[26:27], v[162:163], v[178:179]
	v_fmac_f32_e32 v145, v172, v172
	v_fmac_f32_e32 v145, v173, v173
	v_fmac_f32_e32 v145, v174, v174
	v_fmac_f32_e32 v145, v175, v175
	v_fmac_f32_e32 v145, v176, v176
	v_fmac_f32_e32 v145, v177, v177
	v_fmac_f32_e32 v145, v178, v178
	v_fmac_f32_e32 v145, v179, v179
	v_cvt_pk_bf16_f32 v184, v172, v173
	v_cvt_pk_bf16_f32 v185, v174, v175
	v_cvt_pk_bf16_f32 v186, v176, v177
	v_cvt_pk_bf16_f32 v187, v178, v179
	global_store_dwordx4 v140, v[184:187], s[22:23] offset:256
	s_add_u32 s22, s60, 0x58000
	s_addc_u32 s23, s61, 0
	v_lshlrev_b32_e32 v164, 16, v244
	v_and_b32_e32 v165, 0xffff0000, v244
	v_lshlrev_b32_e32 v166, 16, v245
	v_and_b32_e32 v167, 0xffff0000, v245
	v_lshlrev_b32_e32 v168, 16, v246
	v_and_b32_e32 v169, 0xffff0000, v246
	v_lshlrev_b32_e32 v170, 16, v247
	v_and_b32_e32 v171, 0xffff0000, v247
	v_pk_mul_f32 v[12:13], v[12:13], v[134:135] op_sel:[0,1] op_sel_hi:[1,1]
	v_pk_mul_f32 v[14:15], v[14:15], v[134:135] op_sel:[0,1] op_sel_hi:[1,1]
	v_pk_mul_f32 v[0:1], v[0:1], v[134:135] op_sel:[0,1] op_sel_hi:[1,1]
	v_pk_mul_f32 v[2:3], v[2:3], v[134:135] op_sel:[0,1] op_sel_hi:[1,1]
	v_pk_fma_f32 v[164:165], v[12:13], v[148:149], v[164:165]
	v_pk_fma_f32 v[166:167], v[14:15], v[150:151], v[166:167]
	v_pk_fma_f32 v[168:169], v[0:1], v[152:153], v[168:169]
	v_pk_fma_f32 v[170:171], v[2:3], v[154:155], v[170:171]
	v_mul_f32_e32 v146, v164, v164
	v_fmac_f32_e32 v146, v165, v165
	v_fmac_f32_e32 v146, v166, v166
	v_fmac_f32_e32 v146, v167, v167
	v_fmac_f32_e32 v146, v168, v168
	v_fmac_f32_e32 v146, v169, v169
	v_fmac_f32_e32 v146, v170, v170
	v_fmac_f32_e32 v146, v171, v171
	v_cvt_pk_bf16_f32 v180, v164, v165
	v_cvt_pk_bf16_f32 v181, v166, v167
	v_cvt_pk_bf16_f32 v182, v168, v169
	v_cvt_pk_bf16_f32 v183, v170, v171
	global_store_dwordx4 v140, v[180:183], s[22:23]
	v_lshlrev_b32_e32 v172, 16, v248
	v_and_b32_e32 v173, 0xffff0000, v248
	v_lshlrev_b32_e32 v174, 16, v249
	v_and_b32_e32 v175, 0xffff0000, v249
	v_lshlrev_b32_e32 v176, 16, v250
	v_and_b32_e32 v177, 0xffff0000, v250
	v_lshlrev_b32_e32 v178, 16, v251
	v_and_b32_e32 v179, 0xffff0000, v251
	v_pk_mul_f32 v[4:5], v[4:5], v[134:135] op_sel:[0,1] op_sel_hi:[1,1]
	v_pk_mul_f32 v[6:7], v[6:7], v[134:135] op_sel:[0,1] op_sel_hi:[1,1]
	v_pk_mul_f32 v[8:9], v[8:9], v[134:135] op_sel:[0,1] op_sel_hi:[1,1]
	v_pk_mul_f32 v[10:11], v[10:11], v[134:135] op_sel:[0,1] op_sel_hi:[1,1]
	v_pk_fma_f32 v[172:173], v[4:5], v[156:157], v[172:173]
	v_pk_fma_f32 v[174:175], v[6:7], v[158:159], v[174:175]
	v_pk_fma_f32 v[176:177], v[8:9], v[160:161], v[176:177]
	v_pk_fma_f32 v[178:179], v[10:11], v[162:163], v[178:179]
	v_fmac_f32_e32 v146, v172, v172
	v_fmac_f32_e32 v146, v173, v173
	v_fmac_f32_e32 v146, v174, v174
	v_fmac_f32_e32 v146, v175, v175
	v_fmac_f32_e32 v146, v176, v176
	v_fmac_f32_e32 v146, v177, v177
	v_fmac_f32_e32 v146, v178, v178
	v_fmac_f32_e32 v146, v179, v179
	v_cvt_pk_bf16_f32 v184, v172, v173
	v_cvt_pk_bf16_f32 v185, v174, v175
	v_cvt_pk_bf16_f32 v186, v176, v177
	v_cvt_pk_bf16_f32 v187, v178, v179
	global_store_dwordx4 v140, v[184:187], s[22:23] offset:256
	v_mov_b32_e32 v148, v138
	v_mov_b32_e32 v149, v139
	v_mov_b32_e32 v150, v141
	v_mov_b32_e32 v151, v142
	v_mov_b32_e32 v152, v143
	v_mov_b32_e32 v153, v144
	v_mov_b32_e32 v154, v145
	v_mov_b32_e32 v155, v146
	v_xor_b32_e32 v138, 16, v137
	v_xor_b32_e32 v139, 32, v137
	v_lshlrev_b32_e32 v138, 2, v138
	v_lshlrev_b32_e32 v139, 2, v139
	ds_bpermute_b32 v164, v138, v148
	ds_bpermute_b32 v165, v138, v149
	ds_bpermute_b32 v166, v138, v150
	ds_bpermute_b32 v167, v138, v151
	ds_bpermute_b32 v168, v138, v152
	ds_bpermute_b32 v169, v138, v153
	ds_bpermute_b32 v170, v138, v154
	ds_bpermute_b32 v171, v138, v155
	s_waitcnt lgkmcnt(0)
	v_add_f32_e32 v148, v148, v164
	v_add_f32_e32 v149, v149, v165
	v_add_f32_e32 v150, v150, v166
	v_add_f32_e32 v151, v151, v167
	v_add_f32_e32 v152, v152, v168
	v_add_f32_e32 v153, v153, v169
	v_add_f32_e32 v154, v154, v170
	v_add_f32_e32 v155, v155, v171
	ds_bpermute_b32 v164, v139, v148
	ds_bpermute_b32 v165, v139, v149
	ds_bpermute_b32 v166, v139, v150
	ds_bpermute_b32 v167, v139, v151
	ds_bpermute_b32 v168, v139, v152
	ds_bpermute_b32 v169, v139, v153
	ds_bpermute_b32 v170, v139, v154
	ds_bpermute_b32 v171, v139, v155
	s_waitcnt lgkmcnt(0)
	v_add_f32_e32 v148, v148, v164
	v_add_f32_e32 v149, v149, v165
	v_add_f32_e32 v150, v150, v166
	v_add_f32_e32 v151, v151, v167
	v_add_f32_e32 v152, v152, v168
	v_add_f32_e32 v153, v153, v169
	v_add_f32_e32 v154, v154, v170
	v_add_f32_e32 v155, v155, v171
	s_and_b32 s98, s2, 7
	s_lshl_b32 s98, s98, 3
	s_bfe_u32 s99, s2, 0x30003
	s_or_b32 s98, s98, s99
	s_lshr_b32 s99, s2, 6
	s_mul_i32 s99, s99, 0x42000
	s_lshl_b32 s98, s98, 10
	s_add_u32 s100, s56, s99
	s_addc_u32 s101, s57, 0
	s_add_u32 s100, s100, s98
	s_addc_u32 s101, s101, 0
	v_lshrrev_b32_e32 v158, 8, v136
	v_bfe_u32 v159, v136, 6, 2
	v_and_b32_e32 v160, 15, v136
	v_lshl_add_u32 v160, v158, 6, v160
	v_mul_u32_u24_e32 v159, 0x4200, v159
	v_add_u32_e32 v160, v160, v159
	v_lshlrev_b32_e32 v160, 2, v160
	v_bfe_u32 v161, v136, 4, 2
	v_cmp_eq_u32_e32 vcc, 0, v161
	s_and_saveexec_b64 s[0:1], vcc
	global_store_dword v160, v148, s[100:101]
	global_store_dword v160, v149, s[100:101] offset:64
	global_store_dword v160, v150, s[100:101] offset:128
	global_store_dword v160, v151, s[100:101] offset:192
	global_store_dword v160, v152, s[100:101] offset:512
	global_store_dword v160, v153, s[100:101] offset:576
	global_store_dword v160, v154, s[100:101] offset:640
	global_store_dword v160, v155, s[100:101] offset:704
	s_or_b64 exec, exec, s[0:1]
	v_bfe_u32 v183, v136, 1, 2
	v_lshrrev_b32_e32 v187, 6, v136
	v_lshlrev_b32_e32 v190, 11, v136
	v_lshrrev_b32_e32 v252, 1, v136
	v_and_b32_e32 v132, 48, v136
	v_and_b32_e32 v189, 63, v136
	v_lshrrev_b32_e32 v182, 3, v136
	v_lshlrev_b32_e32 v188, 2, v136
	v_lshl_add_u32 v186, v183, 6, 0
	v_and_b32_e32 v191, 15, v136
	s_cmpk_lt_i32 s2, 0x420
	v_mov_b32_e32 v0, v136
	s_cselect_b64 s[8:9], -1, 0
	s_cmpk_gt_i32 s2, 0x41f
	s_cbranch_scc1 .LBB0_863
	v_and_b32_e32 v4, 63, v0
	v_ashrrev_i32_e32 v0, 5, v0
	v_readlane_b32 s12, v253, 3
	v_and_b32_e32 v5, -2, v0
	v_lshlrev_b32_e32 v0, 4, v4
	v_mov_b32_e32 v1, 0
	v_readlane_b32 s13, v253, 4
	s_mov_b64 s[0:1], 0x1000
	v_readlane_b32 s14, v253, 5
	v_lshl_add_u64 v[2:3], s[12:13], 0, v[0:1]
	v_lshl_add_u64 v[16:17], v[2:3], 0, s[0:1]
	v_and_b32_e32 v2, 64, v137
	v_add_u32_e32 v2, 64, v2
	v_xor_b32_e32 v3, 32, v137
	v_cmp_lt_i32_e64 s[0:1], v3, v2
	v_readlane_b32 s15, v253, 6
	v_readlane_b32 s16, v253, 7
	v_cndmask_b32_e64 v3, v137, v3, s[0:1]
	v_lshlrev_b32_e32 v50, 2, v3
	v_xor_b32_e32 v3, 16, v137
	v_cmp_lt_i32_e64 s[0:1], v3, v2
	v_readlane_b32 s17, v253, 8
	v_readlane_b32 s18, v253, 9
	v_cndmask_b32_e64 v3, v137, v3, s[0:1]
	v_lshlrev_b32_e32 v51, 2, v3
	v_xor_b32_e32 v3, 8, v137
	v_cmp_lt_i32_e64 s[0:1], v3, v2
	v_readlane_b32 s19, v253, 10
	v_readlane_b32 s20, v253, 11
	v_cndmask_b32_e64 v3, v137, v3, s[0:1]
	v_lshlrev_b32_e32 v52, 2, v3
	v_xor_b32_e32 v3, 4, v137
	v_cmp_lt_i32_e64 s[0:1], v3, v2
	v_readlane_b32 s21, v253, 12
	v_readlane_b32 s22, v253, 13
	v_cndmask_b32_e64 v3, v137, v3, s[0:1]
	v_lshlrev_b32_e32 v53, 2, v3
	v_xor_b32_e32 v3, 2, v137
	v_cmp_lt_i32_e64 s[0:1], v3, v2
	v_readlane_b32 s23, v253, 14
	v_readlane_b32 s24, v253, 15
	v_cndmask_b32_e64 v3, v137, v3, s[0:1]
	v_readlane_b32 s25, v253, 16
	v_readlane_b32 s26, v253, 17
	v_readlane_b32 s27, v253, 18
	v_mul_u32_u24_e32 v0, 0x4200, v4
	v_lshlrev_b32_e32 v54, 2, v3
	v_xor_b32_e32 v3, 1, v137
	v_cmp_lt_i32_e64 s[0:1], v3, v2
	v_lshlrev_b32_e32 v0, 2, v0
	v_readlane_b32 s12, v253, 51
	v_cndmask_b32_e64 v2, v137, v3, s[0:1]
	v_lshl_add_u64 v[18:19], s[44:45], 0, v[0:1]
	v_lshlrev_b32_e32 v0, 3, v4
	v_readlane_b32 s13, v253, 52
	v_readlane_b32 s14, v253, 53
	v_readlane_b32 s15, v253, 54
	v_cmp_gt_u32_e32 vcc, 16, v4
	v_lshlrev_b32_e32 v55, 2, v2
	v_cmp_eq_u32_e64 s[0:1], 0, v4
	v_lshl_add_u64 v[20:21], s[60:61], 0, v[0:1]
	v_lshl_add_u64 v[22:23], s[14:15], 0, v[0:1]
	v_lshl_add_u64 v[24:25], s[58:59], 0, v[0:1]
	v_lshl_add_u32 v26, s2, 4, v5
	s_lshl_b32 s3, s38, 4
	v_mov_b32_e32 v56, 0x358637bd
	s_mov_b32 s12, 0x800000
	s_mov_b32 s13, s2
	v_readlane_b32 s16, v253, 55
	v_readlane_b32 s17, v253, 56
	v_readlane_b32 s18, v253, 57
	v_readlane_b32 s19, v253, 58
	v_readlane_b32 s20, v253, 59
	v_readlane_b32 s21, v253, 60
	v_readlane_b32 s22, v253, 61
	v_readlane_b32 s23, v253, 62
	v_readlane_b32 s24, v253, 63
	v_readlane_b32 s25, v254, 0
	v_readlane_b32 s26, v254, 1
	v_readlane_b32 s27, v254, 2
	s_addk_i32 s13, 0x400
	v_add_u32_e32 v26, 0x4000, v26
	s_cmpk_lt_i32 s13, 0x420
	s_cbranch_scc0 .LBB0_863
	s_branch .LBB0_855

.LBB0_1243:
	s_or_b64 exec, exec, s[0:1]
	s_waitcnt lgkmcnt(0)
	s_barrier
	s_and_b32 s98, s2, 7
	s_lshl_b32 s98, s98, 3
	s_bfe_u32 s99, s2, 0x30003
	s_or_b32 s98, s98, s99
	s_lshr_b32 s99, s2, 6
	v_and_b32_e32 v172, 0xff, v136
	v_lshrrev_b32_e32 v173, 8, v136
	v_mul_u32_u24_e32 v173, 0x84000, v173
	v_lshl_add_u32 v172, v172, 2, v173
	s_lshl_b32 s24, s98, 10
	s_add_u32 s18, s44, s24
	s_addc_u32 s19, s45, 0
	global_load_dword v164, v172, s[18:19]
	s_add_u32 s18, s18, 0x10800
	s_addc_u32 s19, s19, 0
	global_load_dword v165, v172, s[18:19]
	s_add_u32 s18, s18, 0x10800
	s_addc_u32 s19, s19, 0
	global_load_dword v166, v172, s[18:19]
	s_add_u32 s18, s18, 0x10800
	s_addc_u32 s19, s19, 0
	global_load_dword v167, v172, s[18:19]
	s_add_u32 s18, s18, 0x10800
	s_addc_u32 s19, s19, 0
	global_load_dword v168, v172, s[18:19]
	s_add_u32 s18, s18, 0x10800
	s_addc_u32 s19, s19, 0
	global_load_dword v169, v172, s[18:19]
	s_add_u32 s18, s18, 0x10800
	s_addc_u32 s19, s19, 0
	global_load_dword v170, v172, s[18:19]
	s_add_u32 s18, s18, 0x10800
	s_addc_u32 s19, s19, 0
	global_load_dword v171, v172, s[18:19]
	v_lshrrev_b32_e32 v141, 8, v136
	v_and_b32_e32 v142, 15, v136
	v_lshl_add_u32 v141, v141, 6, v142
	v_bfe_u32 v144, v136, 6, 2
	v_bfe_u32 v145, v136, 4, 2
	v_lshlrev_b32_e32 v144, 5, v144
	v_lshl_add_u32 v144, v145, 3, v144
	s_lshl_b32 s24, s99, 8
	v_add_u32_e32 v144, s24, v144
	s_lshl_b32 s25, s98, 8
	v_add_u32_e32 v145, s25, v141
	v_lshl_add_u32 v146, v145, 10, v144
	v_lshlrev_b32_e32 v140, 1, v146
	v_lshlrev_b32_e32 v147, 2, v144
	v_readlane_b32 s18, v253, 3
	v_readlane_b32 s19, v253, 4
	s_mov_b32 s20, s60
	s_mov_b32 s21, s61
	s_nop 4
	s_add_u32 s18, s18, 0x3000
	s_addc_u32 s19, s19, 0
	global_load_dwordx4 v[148:151], v147, s[18:19]
	global_load_dwordx4 v[152:155], v147, s[18:19] offset:16
	global_load_dwordx4 v[156:159], v147, s[18:19] offset:512
	global_load_dwordx4 v[160:163], v147, s[18:19] offset:528
	s_add_u32 s22, s20, 0x0
	s_addc_u32 s23, s21, 0
	global_load_dwordx4 v[188:191], v140, s[22:23] nt
	global_load_dwordx4 v[192:195], v140, s[22:23] offset:256 nt
	s_add_u32 s22, s20, 0x8000
	s_addc_u32 s23, s21, 0
	global_load_dwordx4 v[196:199], v140, s[22:23] nt
	global_load_dwordx4 v[200:203], v140, s[22:23] offset:256 nt
	s_add_u32 s22, s20, 0x10000
	s_addc_u32 s23, s21, 0
	global_load_dwordx4 v[204:207], v140, s[22:23] nt
	global_load_dwordx4 v[208:211], v140, s[22:23] offset:256 nt
	s_add_u32 s22, s20, 0x18000
	s_addc_u32 s23, s21, 0
	global_load_dwordx4 v[212:215], v140, s[22:23] nt
	global_load_dwordx4 v[216:219], v140, s[22:23] offset:256 nt
	s_add_u32 s22, s20, 0x40000
	s_addc_u32 s23, s21, 0
	global_load_dwordx4 v[220:223], v140, s[22:23] nt
	global_load_dwordx4 v[224:227], v140, s[22:23] offset:256 nt
	s_add_u32 s22, s20, 0x48000
	s_addc_u32 s23, s21, 0
	global_load_dwordx4 v[228:231], v140, s[22:23] nt
	global_load_dwordx4 v[232:235], v140, s[22:23] offset:256 nt
	s_add_u32 s22, s20, 0x50000
	s_addc_u32 s23, s21, 0
	global_load_dwordx4 v[236:239], v140, s[22:23] nt
	global_load_dwordx4 v[240:243], v140, s[22:23] offset:256 nt
	s_add_u32 s22, s20, 0x58000
	s_addc_u32 s23, s21, 0
	global_load_dwordx4 v[244:247], v140, s[22:23] nt
	global_load_dwordx4 v[248:251], v140, s[22:23] offset:256 nt
	s_waitcnt vmcnt(20)
	v_add_f32_e32 v164, v164, v165
	v_add_f32_e32 v164, v164, v166
	v_add_f32_e32 v164, v164, v167
	v_add_f32_e32 v164, v164, v168
	v_add_f32_e32 v164, v164, v169
	v_add_f32_e32 v164, v164, v170
	v_add_f32_e32 v164, v164, v171
	v_lshlrev_b32_e32 v173, 2, v136
	ds_write_b32 v173, v164
	s_waitcnt lgkmcnt(0)
	s_barrier
	v_lshlrev_b32_e32 v142, 2, v141
	ds_read_b32 v128, v142 offset:0
	ds_read_b32 v174, v142 offset:1024
	ds_read_b32 v129, v142 offset:64
	ds_read_b32 v175, v142 offset:1088
	ds_read_b32 v130, v142 offset:128
	ds_read_b32 v176, v142 offset:1152
	ds_read_b32 v131, v142 offset:192
	ds_read_b32 v177, v142 offset:1216
	ds_read_b32 v132, v142 offset:512
	ds_read_b32 v178, v142 offset:1536
	ds_read_b32 v133, v142 offset:576
	ds_read_b32 v179, v142 offset:1600
	ds_read_b32 v134, v142 offset:640
	ds_read_b32 v180, v142 offset:1664
	ds_read_b32 v135, v142 offset:704
	ds_read_b32 v181, v142 offset:1728
	s_waitcnt lgkmcnt(0)
	s_mov_b32 s101, 0x3a800000
	v_mov_b32_e32 v143, 0x358637bd
	v_add_f32_e32 v128, v128, v174
	v_add_f32_e32 v129, v129, v175
	v_add_f32_e32 v130, v130, v176
	v_add_f32_e32 v131, v131, v177
	v_add_f32_e32 v132, v132, v178
	v_add_f32_e32 v133, v133, v179
	v_add_f32_e32 v134, v134, v180
	v_add_f32_e32 v135, v135, v181
	v_fma_f32 v128, v128, s101, v143
	v_fma_f32 v129, v129, s101, v143
	v_fma_f32 v130, v130, s101, v143
	v_fma_f32 v131, v131, s101, v143
	v_fma_f32 v132, v132, s101, v143
	v_fma_f32 v133, v133, s101, v143
	v_fma_f32 v134, v134, s101, v143
	v_fma_f32 v135, v135, s101, v143
	v_rsq_f32_e32 v128, v128
	v_rsq_f32_e32 v129, v129
	v_rsq_f32_e32 v130, v130
	v_rsq_f32_e32 v131, v131
	v_rsq_f32_e32 v132, v132
	v_rsq_f32_e32 v133, v133
	v_rsq_f32_e32 v134, v134
	v_rsq_f32_e32 v135, v135
	s_waitcnt vmcnt(0)
	s_add_u32 s22, s64, 0x0
	s_addc_u32 s23, s65, 0
	v_lshlrev_b32_e32 v164, 16, v188
	v_and_b32_e32 v165, 0xffff0000, v188
	v_lshlrev_b32_e32 v166, 16, v189
	v_and_b32_e32 v167, 0xffff0000, v189
	v_lshlrev_b32_e32 v168, 16, v190
	v_and_b32_e32 v169, 0xffff0000, v190
	v_lshlrev_b32_e32 v170, 16, v191
	v_and_b32_e32 v171, 0xffff0000, v191
	v_pk_mul_f32 v[124:125], v[124:125], v[128:129] op_sel_hi:[1,0]
	v_pk_mul_f32 v[126:127], v[126:127], v[128:129] op_sel_hi:[1,0]
	v_pk_mul_f32 v[112:113], v[112:113], v[128:129] op_sel_hi:[1,0]
	v_pk_mul_f32 v[114:115], v[114:115], v[128:129] op_sel_hi:[1,0]
	v_pk_fma_f32 v[164:165], v[124:125], v[148:149], v[164:165]
	v_pk_fma_f32 v[166:167], v[126:127], v[150:151], v[166:167]
	v_pk_fma_f32 v[168:169], v[112:113], v[152:153], v[168:169]
	v_pk_fma_f32 v[170:171], v[114:115], v[154:155], v[170:171]
	v_mul_f32_e32 v138, v164, v164
	v_fmac_f32_e32 v138, v165, v165
	v_fmac_f32_e32 v138, v166, v166
	v_fmac_f32_e32 v138, v167, v167
	v_fmac_f32_e32 v138, v168, v168
	v_fmac_f32_e32 v138, v169, v169
	v_fmac_f32_e32 v138, v170, v170
	v_fmac_f32_e32 v138, v171, v171
	v_cvt_pk_bf16_f32 v180, v164, v165
	v_cvt_pk_bf16_f32 v181, v166, v167
	v_cvt_pk_bf16_f32 v182, v168, v169
	v_cvt_pk_bf16_f32 v183, v170, v171
	global_store_dwordx4 v140, v[180:183], s[22:23]
	v_lshlrev_b32_e32 v172, 16, v192
	v_and_b32_e32 v173, 0xffff0000, v192
	v_lshlrev_b32_e32 v174, 16, v193
	v_and_b32_e32 v175, 0xffff0000, v193
	v_lshlrev_b32_e32 v176, 16, v194
	v_and_b32_e32 v177, 0xffff0000, v194
	v_lshlrev_b32_e32 v178, 16, v195
	v_and_b32_e32 v179, 0xffff0000, v195
	v_pk_mul_f32 v[120:121], v[120:121], v[128:129] op_sel_hi:[1,0]
	v_pk_mul_f32 v[122:123], v[122:123], v[128:129] op_sel_hi:[1,0]
	v_pk_mul_f32 v[116:117], v[116:117], v[128:129] op_sel_hi:[1,0]
	v_pk_mul_f32 v[118:119], v[118:119], v[128:129] op_sel_hi:[1,0]
	v_pk_fma_f32 v[172:173], v[120:121], v[156:157], v[172:173]
	v_pk_fma_f32 v[174:175], v[122:123], v[158:159], v[174:175]
	v_pk_fma_f32 v[176:177], v[116:117], v[160:161], v[176:177]
	v_pk_fma_f32 v[178:179], v[118:119], v[162:163], v[178:179]
	v_fmac_f32_e32 v138, v172, v172
	v_fmac_f32_e32 v138, v173, v173
	v_fmac_f32_e32 v138, v174, v174
	v_fmac_f32_e32 v138, v175, v175
	v_fmac_f32_e32 v138, v176, v176
	v_fmac_f32_e32 v138, v177, v177
	v_fmac_f32_e32 v138, v178, v178
	v_fmac_f32_e32 v138, v179, v179
	v_cvt_pk_bf16_f32 v184, v172, v173
	v_cvt_pk_bf16_f32 v185, v174, v175
	v_cvt_pk_bf16_f32 v186, v176, v177
	v_cvt_pk_bf16_f32 v187, v178, v179
	global_store_dwordx4 v140, v[184:187], s[22:23] offset:256
	s_add_u32 s22, s64, 0x8000
	s_addc_u32 s23, s65, 0
	v_lshlrev_b32_e32 v164, 16, v196
	v_and_b32_e32 v165, 0xffff0000, v196
	v_lshlrev_b32_e32 v166, 16, v197
	v_and_b32_e32 v167, 0xffff0000, v197
	v_lshlrev_b32_e32 v168, 16, v198
	v_and_b32_e32 v169, 0xffff0000, v198
	v_lshlrev_b32_e32 v170, 16, v199
	v_and_b32_e32 v171, 0xffff0000, v199
	v_pk_mul_f32 v[108:109], v[108:109], v[128:129] op_sel:[0,1] op_sel_hi:[1,1]
	v_pk_mul_f32 v[110:111], v[110:111], v[128:129] op_sel:[0,1] op_sel_hi:[1,1]
	v_pk_mul_f32 v[96:97], v[96:97], v[128:129] op_sel:[0,1] op_sel_hi:[1,1]
	v_pk_mul_f32 v[98:99], v[98:99], v[128:129] op_sel:[0,1] op_sel_hi:[1,1]
	v_pk_fma_f32 v[164:165], v[108:109], v[148:149], v[164:165]
	v_pk_fma_f32 v[166:167], v[110:111], v[150:151], v[166:167]
	v_pk_fma_f32 v[168:169], v[96:97], v[152:153], v[168:169]
	v_pk_fma_f32 v[170:171], v[98:99], v[154:155], v[170:171]
	v_mul_f32_e32 v139, v164, v164
	v_fmac_f32_e32 v139, v165, v165
	v_fmac_f32_e32 v139, v166, v166
	v_fmac_f32_e32 v139, v167, v167
	v_fmac_f32_e32 v139, v168, v168
	v_fmac_f32_e32 v139, v169, v169
	v_fmac_f32_e32 v139, v170, v170
	v_fmac_f32_e32 v139, v171, v171
	v_cvt_pk_bf16_f32 v180, v164, v165
	v_cvt_pk_bf16_f32 v181, v166, v167
	v_cvt_pk_bf16_f32 v182, v168, v169
	v_cvt_pk_bf16_f32 v183, v170, v171
	global_store_dwordx4 v140, v[180:183], s[22:23]
	v_lshlrev_b32_e32 v172, 16, v200
	v_and_b32_e32 v173, 0xffff0000, v200
	v_lshlrev_b32_e32 v174, 16, v201
	v_and_b32_e32 v175, 0xffff0000, v201
	v_lshlrev_b32_e32 v176, 16, v202
	v_and_b32_e32 v177, 0xffff0000, v202
	v_lshlrev_b32_e32 v178, 16, v203
	v_and_b32_e32 v179, 0xffff0000, v203
	v_pk_mul_f32 v[100:101], v[100:101], v[128:129] op_sel:[0,1] op_sel_hi:[1,1]
	v_pk_mul_f32 v[102:103], v[102:103], v[128:129] op_sel:[0,1] op_sel_hi:[1,1]
	v_pk_mul_f32 v[104:105], v[104:105], v[128:129] op_sel:[0,1] op_sel_hi:[1,1]
	v_pk_mul_f32 v[106:107], v[106:107], v[128:129] op_sel:[0,1] op_sel_hi:[1,1]
	v_pk_fma_f32 v[172:173], v[100:101], v[156:157], v[172:173]
	v_pk_fma_f32 v[174:175], v[102:103], v[158:159], v[174:175]
	v_pk_fma_f32 v[176:177], v[104:105], v[160:161], v[176:177]
	v_pk_fma_f32 v[178:179], v[106:107], v[162:163], v[178:179]
	v_fmac_f32_e32 v139, v172, v172
	v_fmac_f32_e32 v139, v173, v173
	v_fmac_f32_e32 v139, v174, v174
	v_fmac_f32_e32 v139, v175, v175
	v_fmac_f32_e32 v139, v176, v176
	v_fmac_f32_e32 v139, v177, v177
	v_fmac_f32_e32 v139, v178, v178
	v_fmac_f32_e32 v139, v179, v179
	v_cvt_pk_bf16_f32 v184, v172, v173
	v_cvt_pk_bf16_f32 v185, v174, v175
	v_cvt_pk_bf16_f32 v186, v176, v177
	v_cvt_pk_bf16_f32 v187, v178, v179
	global_store_dwordx4 v140, v[184:187], s[22:23] offset:256
	s_add_u32 s22, s64, 0x10000
	s_addc_u32 s23, s65, 0
	v_lshlrev_b32_e32 v164, 16, v204
	v_and_b32_e32 v165, 0xffff0000, v204
	v_lshlrev_b32_e32 v166, 16, v205
	v_and_b32_e32 v167, 0xffff0000, v205
	v_lshlrev_b32_e32 v168, 16, v206
	v_and_b32_e32 v169, 0xffff0000, v206
	v_lshlrev_b32_e32 v170, 16, v207
	v_and_b32_e32 v171, 0xffff0000, v207
	v_pk_mul_f32 v[92:93], v[92:93], v[130:131] op_sel_hi:[1,0]
	v_pk_mul_f32 v[94:95], v[94:95], v[130:131] op_sel_hi:[1,0]
	v_pk_mul_f32 v[80:81], v[80:81], v[130:131] op_sel_hi:[1,0]
	v_pk_mul_f32 v[82:83], v[82:83], v[130:131] op_sel_hi:[1,0]
	v_pk_fma_f32 v[164:165], v[92:93], v[148:149], v[164:165]
	v_pk_fma_f32 v[166:167], v[94:95], v[150:151], v[166:167]
	v_pk_fma_f32 v[168:169], v[80:81], v[152:153], v[168:169]
	v_pk_fma_f32 v[170:171], v[82:83], v[154:155], v[170:171]
	v_mul_f32_e32 v141, v164, v164
	v_fmac_f32_e32 v141, v165, v165
	v_fmac_f32_e32 v141, v166, v166
	v_fmac_f32_e32 v141, v167, v167
	v_fmac_f32_e32 v141, v168, v168
	v_fmac_f32_e32 v141, v169, v169
	v_fmac_f32_e32 v141, v170, v170
	v_fmac_f32_e32 v141, v171, v171
	v_cvt_pk_bf16_f32 v180, v164, v165
	v_cvt_pk_bf16_f32 v181, v166, v167
	v_cvt_pk_bf16_f32 v182, v168, v169
	v_cvt_pk_bf16_f32 v183, v170, v171
	global_store_dwordx4 v140, v[180:183], s[22:23]
	v_lshlrev_b32_e32 v172, 16, v208
	v_and_b32_e32 v173, 0xffff0000, v208
	v_lshlrev_b32_e32 v174, 16, v209
	v_and_b32_e32 v175, 0xffff0000, v209
	v_lshlrev_b32_e32 v176, 16, v210
	v_and_b32_e32 v177, 0xffff0000, v210
	v_lshlrev_b32_e32 v178, 16, v211
	v_and_b32_e32 v179, 0xffff0000, v211
	v_pk_mul_f32 v[84:85], v[84:85], v[130:131] op_sel_hi:[1,0]
	v_pk_mul_f32 v[86:87], v[86:87], v[130:131] op_sel_hi:[1,0]
	v_pk_mul_f32 v[88:89], v[88:89], v[130:131] op_sel_hi:[1,0]
	v_pk_mul_f32 v[90:91], v[90:91], v[130:131] op_sel_hi:[1,0]
	v_pk_fma_f32 v[172:173], v[84:85], v[156:157], v[172:173]
	v_pk_fma_f32 v[174:175], v[86:87], v[158:159], v[174:175]
	v_pk_fma_f32 v[176:177], v[88:89], v[160:161], v[176:177]
	v_pk_fma_f32 v[178:179], v[90:91], v[162:163], v[178:179]
	v_fmac_f32_e32 v141, v172, v172
	v_fmac_f32_e32 v141, v173, v173
	v_fmac_f32_e32 v141, v174, v174
	v_fmac_f32_e32 v141, v175, v175
	v_fmac_f32_e32 v141, v176, v176
	v_fmac_f32_e32 v141, v177, v177
	v_fmac_f32_e32 v141, v178, v178
	v_fmac_f32_e32 v141, v179, v179
	v_cvt_pk_bf16_f32 v184, v172, v173
	v_cvt_pk_bf16_f32 v185, v174, v175
	v_cvt_pk_bf16_f32 v186, v176, v177
	v_cvt_pk_bf16_f32 v187, v178, v179
	global_store_dwordx4 v140, v[184:187], s[22:23] offset:256
	s_add_u32 s22, s64, 0x18000
	s_addc_u32 s23, s65, 0
	v_lshlrev_b32_e32 v164, 16, v212
	v_and_b32_e32 v165, 0xffff0000, v212
	v_lshlrev_b32_e32 v166, 16, v213
	v_and_b32_e32 v167, 0xffff0000, v213
	v_lshlrev_b32_e32 v168, 16, v214
	v_and_b32_e32 v169, 0xffff0000, v214
	v_lshlrev_b32_e32 v170, 16, v215
	v_and_b32_e32 v171, 0xffff0000, v215
	v_pk_mul_f32 v[76:77], v[76:77], v[130:131] op_sel:[0,1] op_sel_hi:[1,1]
	v_pk_mul_f32 v[78:79], v[78:79], v[130:131] op_sel:[0,1] op_sel_hi:[1,1]
	v_pk_mul_f32 v[64:65], v[64:65], v[130:131] op_sel:[0,1] op_sel_hi:[1,1]
	v_pk_mul_f32 v[66:67], v[66:67], v[130:131] op_sel:[0,1] op_sel_hi:[1,1]
	v_pk_fma_f32 v[164:165], v[76:77], v[148:149], v[164:165]
	v_pk_fma_f32 v[166:167], v[78:79], v[150:151], v[166:167]
	v_pk_fma_f32 v[168:169], v[64:65], v[152:153], v[168:169]
	v_pk_fma_f32 v[170:171], v[66:67], v[154:155], v[170:171]
	v_mul_f32_e32 v142, v164, v164
	v_fmac_f32_e32 v142, v165, v165
	v_fmac_f32_e32 v142, v166, v166
	v_fmac_f32_e32 v142, v167, v167
	v_fmac_f32_e32 v142, v168, v168
	v_fmac_f32_e32 v142, v169, v169
	v_fmac_f32_e32 v142, v170, v170
	v_fmac_f32_e32 v142, v171, v171
	v_cvt_pk_bf16_f32 v180, v164, v165
	v_cvt_pk_bf16_f32 v181, v166, v167
	v_cvt_pk_bf16_f32 v182, v168, v169
	v_cvt_pk_bf16_f32 v183, v170, v171
	global_store_dwordx4 v140, v[180:183], s[22:23]
	v_lshlrev_b32_e32 v172, 16, v216
	v_and_b32_e32 v173, 0xffff0000, v216
	v_lshlrev_b32_e32 v174, 16, v217
	v_and_b32_e32 v175, 0xffff0000, v217
	v_lshlrev_b32_e32 v176, 16, v218
	v_and_b32_e32 v177, 0xffff0000, v218
	v_lshlrev_b32_e32 v178, 16, v219
	v_and_b32_e32 v179, 0xffff0000, v219
	v_pk_mul_f32 v[68:69], v[68:69], v[130:131] op_sel:[0,1] op_sel_hi:[1,1]
	v_pk_mul_f32 v[70:71], v[70:71], v[130:131] op_sel:[0,1] op_sel_hi:[1,1]
	v_pk_mul_f32 v[72:73], v[72:73], v[130:131] op_sel:[0,1] op_sel_hi:[1,1]
	v_pk_mul_f32 v[74:75], v[74:75], v[130:131] op_sel:[0,1] op_sel_hi:[1,1]
	v_pk_fma_f32 v[172:173], v[68:69], v[156:157], v[172:173]
	v_pk_fma_f32 v[174:175], v[70:71], v[158:159], v[174:175]
	v_pk_fma_f32 v[176:177], v[72:73], v[160:161], v[176:177]
	v_pk_fma_f32 v[178:179], v[74:75], v[162:163], v[178:179]
	v_fmac_f32_e32 v142, v172, v172
	v_fmac_f32_e32 v142, v173, v173
	v_fmac_f32_e32 v142, v174, v174
	v_fmac_f32_e32 v142, v175, v175
	v_fmac_f32_e32 v142, v176, v176
	v_fmac_f32_e32 v142, v177, v177
	v_fmac_f32_e32 v142, v178, v178
	v_fmac_f32_e32 v142, v179, v179
	v_cvt_pk_bf16_f32 v184, v172, v173
	v_cvt_pk_bf16_f32 v185, v174, v175
	v_cvt_pk_bf16_f32 v186, v176, v177
	v_cvt_pk_bf16_f32 v187, v178, v179
	global_store_dwordx4 v140, v[184:187], s[22:23] offset:256
	s_add_u32 s22, s64, 0x40000
	s_addc_u32 s23, s65, 0
	v_lshlrev_b32_e32 v164, 16, v220
	v_and_b32_e32 v165, 0xffff0000, v220
	v_lshlrev_b32_e32 v166, 16, v221
	v_and_b32_e32 v167, 0xffff0000, v221
	v_lshlrev_b32_e32 v168, 16, v222
	v_and_b32_e32 v169, 0xffff0000, v222
	v_lshlrev_b32_e32 v170, 16, v223
	v_and_b32_e32 v171, 0xffff0000, v223
	v_pk_mul_f32 v[60:61], v[60:61], v[132:133] op_sel_hi:[1,0]
	v_pk_mul_f32 v[62:63], v[62:63], v[132:133] op_sel_hi:[1,0]
	v_pk_mul_f32 v[48:49], v[48:49], v[132:133] op_sel_hi:[1,0]
	v_pk_mul_f32 v[50:51], v[50:51], v[132:133] op_sel_hi:[1,0]
	v_pk_fma_f32 v[164:165], v[60:61], v[148:149], v[164:165]
	v_pk_fma_f32 v[166:167], v[62:63], v[150:151], v[166:167]
	v_pk_fma_f32 v[168:169], v[48:49], v[152:153], v[168:169]
	v_pk_fma_f32 v[170:171], v[50:51], v[154:155], v[170:171]
	v_mul_f32_e32 v143, v164, v164
	v_fmac_f32_e32 v143, v165, v165
	v_fmac_f32_e32 v143, v166, v166
	v_fmac_f32_e32 v143, v167, v167
	v_fmac_f32_e32 v143, v168, v168
	v_fmac_f32_e32 v143, v169, v169
	v_fmac_f32_e32 v143, v170, v170
	v_fmac_f32_e32 v143, v171, v171
	v_cvt_pk_bf16_f32 v180, v164, v165
	v_cvt_pk_bf16_f32 v181, v166, v167
	v_cvt_pk_bf16_f32 v182, v168, v169
	v_cvt_pk_bf16_f32 v183, v170, v171
	global_store_dwordx4 v140, v[180:183], s[22:23]
	v_lshlrev_b32_e32 v172, 16, v224
	v_and_b32_e32 v173, 0xffff0000, v224
	v_lshlrev_b32_e32 v174, 16, v225
	v_and_b32_e32 v175, 0xffff0000, v225
	v_lshlrev_b32_e32 v176, 16, v226
	v_and_b32_e32 v177, 0xffff0000, v226
	v_lshlrev_b32_e32 v178, 16, v227
	v_and_b32_e32 v179, 0xffff0000, v227
	v_pk_mul_f32 v[52:53], v[52:53], v[132:133] op_sel_hi:[1,0]
	v_pk_mul_f32 v[54:55], v[54:55], v[132:133] op_sel_hi:[1,0]
	v_pk_mul_f32 v[56:57], v[56:57], v[132:133] op_sel_hi:[1,0]
	v_pk_mul_f32 v[58:59], v[58:59], v[132:133] op_sel_hi:[1,0]
	v_pk_fma_f32 v[172:173], v[52:53], v[156:157], v[172:173]
	v_pk_fma_f32 v[174:175], v[54:55], v[158:159], v[174:175]
	v_pk_fma_f32 v[176:177], v[56:57], v[160:161], v[176:177]
	v_pk_fma_f32 v[178:179], v[58:59], v[162:163], v[178:179]
	v_fmac_f32_e32 v143, v172, v172
	v_fmac_f32_e32 v143, v173, v173
	v_fmac_f32_e32 v143, v174, v174
	v_fmac_f32_e32 v143, v175, v175
	v_fmac_f32_e32 v143, v176, v176
	v_fmac_f32_e32 v143, v177, v177
	v_fmac_f32_e32 v143, v178, v178
	v_fmac_f32_e32 v143, v179, v179
	v_cvt_pk_bf16_f32 v184, v172, v173
	v_cvt_pk_bf16_f32 v185, v174, v175
	v_cvt_pk_bf16_f32 v186, v176, v177
	v_cvt_pk_bf16_f32 v187, v178, v179
	global_store_dwordx4 v140, v[184:187], s[22:23] offset:256
	s_add_u32 s22, s64, 0x48000
	s_addc_u32 s23, s65, 0
	v_lshlrev_b32_e32 v164, 16, v228
	v_and_b32_e32 v165, 0xffff0000, v228
	v_lshlrev_b32_e32 v166, 16, v229
	v_and_b32_e32 v167, 0xffff0000, v229
	v_lshlrev_b32_e32 v168, 16, v230
	v_and_b32_e32 v169, 0xffff0000, v230
	v_lshlrev_b32_e32 v170, 16, v231
	v_and_b32_e32 v171, 0xffff0000, v231
	v_pk_mul_f32 v[44:45], v[44:45], v[132:133] op_sel:[0,1] op_sel_hi:[1,1]
	v_pk_mul_f32 v[46:47], v[46:47], v[132:133] op_sel:[0,1] op_sel_hi:[1,1]
	v_pk_mul_f32 v[32:33], v[32:33], v[132:133] op_sel:[0,1] op_sel_hi:[1,1]
	v_pk_mul_f32 v[34:35], v[34:35], v[132:133] op_sel:[0,1] op_sel_hi:[1,1]
	v_pk_fma_f32 v[164:165], v[44:45], v[148:149], v[164:165]
	v_pk_fma_f32 v[166:167], v[46:47], v[150:151], v[166:167]
	v_pk_fma_f32 v[168:169], v[32:33], v[152:153], v[168:169]
	v_pk_fma_f32 v[170:171], v[34:35], v[154:155], v[170:171]
	v_mul_f32_e32 v144, v164, v164
	v_fmac_f32_e32 v144, v165, v165
	v_fmac_f32_e32 v144, v166, v166
	v_fmac_f32_e32 v144, v167, v167
	v_fmac_f32_e32 v144, v168, v168
	v_fmac_f32_e32 v144, v169, v169
	v_fmac_f32_e32 v144, v170, v170
	v_fmac_f32_e32 v144, v171, v171
	v_cvt_pk_bf16_f32 v180, v164, v165
	v_cvt_pk_bf16_f32 v181, v166, v167
	v_cvt_pk_bf16_f32 v182, v168, v169
	v_cvt_pk_bf16_f32 v183, v170, v171
	global_store_dwordx4 v140, v[180:183], s[22:23]
	v_lshlrev_b32_e32 v172, 16, v232
	v_and_b32_e32 v173, 0xffff0000, v232
	v_lshlrev_b32_e32 v174, 16, v233
	v_and_b32_e32 v175, 0xffff0000, v233
	v_lshlrev_b32_e32 v176, 16, v234
	v_and_b32_e32 v177, 0xffff0000, v234
	v_lshlrev_b32_e32 v178, 16, v235
	v_and_b32_e32 v179, 0xffff0000, v235
	v_pk_mul_f32 v[36:37], v[36:37], v[132:133] op_sel:[0,1] op_sel_hi:[1,1]
	v_pk_mul_f32 v[38:39], v[38:39], v[132:133] op_sel:[0,1] op_sel_hi:[1,1]
	v_pk_mul_f32 v[40:41], v[40:41], v[132:133] op_sel:[0,1] op_sel_hi:[1,1]
	v_pk_mul_f32 v[42:43], v[42:43], v[132:133] op_sel:[0,1] op_sel_hi:[1,1]
	v_pk_fma_f32 v[172:173], v[36:37], v[156:157], v[172:173]
	v_pk_fma_f32 v[174:175], v[38:39], v[158:159], v[174:175]
	v_pk_fma_f32 v[176:177], v[40:41], v[160:161], v[176:177]
	v_pk_fma_f32 v[178:179], v[42:43], v[162:163], v[178:179]
	v_fmac_f32_e32 v144, v172, v172
	v_fmac_f32_e32 v144, v173, v173
	v_fmac_f32_e32 v144, v174, v174
	v_fmac_f32_e32 v144, v175, v175
	v_fmac_f32_e32 v144, v176, v176
	v_fmac_f32_e32 v144, v177, v177
	v_fmac_f32_e32 v144, v178, v178
	v_fmac_f32_e32 v144, v179, v179
	v_cvt_pk_bf16_f32 v184, v172, v173
	v_cvt_pk_bf16_f32 v185, v174, v175
	v_cvt_pk_bf16_f32 v186, v176, v177
	v_cvt_pk_bf16_f32 v187, v178, v179
	global_store_dwordx4 v140, v[184:187], s[22:23] offset:256
	s_add_u32 s22, s64, 0x50000
	s_addc_u32 s23, s65, 0
	v_lshlrev_b32_e32 v164, 16, v236
	v_and_b32_e32 v165, 0xffff0000, v236
	v_lshlrev_b32_e32 v166, 16, v237
	v_and_b32_e32 v167, 0xffff0000, v237
	v_lshlrev_b32_e32 v168, 16, v238
	v_and_b32_e32 v169, 0xffff0000, v238
	v_lshlrev_b32_e32 v170, 16, v239
	v_and_b32_e32 v171, 0xffff0000, v239
	v_pk_mul_f32 v[28:29], v[28:29], v[134:135] op_sel_hi:[1,0]
	v_pk_mul_f32 v[30:31], v[30:31], v[134:135] op_sel_hi:[1,0]
	v_pk_mul_f32 v[16:17], v[16:17], v[134:135] op_sel_hi:[1,0]
	v_pk_mul_f32 v[18:19], v[18:19], v[134:135] op_sel_hi:[1,0]
	v_pk_fma_f32 v[164:165], v[28:29], v[148:149], v[164:165]
	v_pk_fma_f32 v[166:167], v[30:31], v[150:151], v[166:167]
	v_pk_fma_f32 v[168:169], v[16:17], v[152:153], v[168:169]
	v_pk_fma_f32 v[170:171], v[18:19], v[154:155], v[170:171]
	v_mul_f32_e32 v145, v164, v164
	v_fmac_f32_e32 v145, v165, v165
	v_fmac_f32_e32 v145, v166, v166
	v_fmac_f32_e32 v145, v167, v167
	v_fmac_f32_e32 v145, v168, v168
	v_fmac_f32_e32 v145, v169, v169
	v_fmac_f32_e32 v145, v170, v170
	v_fmac_f32_e32 v145, v171, v171
	v_cvt_pk_bf16_f32 v180, v164, v165
	v_cvt_pk_bf16_f32 v181, v166, v167
	v_cvt_pk_bf16_f32 v182, v168, v169
	v_cvt_pk_bf16_f32 v183, v170, v171
	global_store_dwordx4 v140, v[180:183], s[22:23]
	v_lshlrev_b32_e32 v172, 16, v240
	v_and_b32_e32 v173, 0xffff0000, v240
	v_lshlrev_b32_e32 v174, 16, v241
	v_and_b32_e32 v175, 0xffff0000, v241
	v_lshlrev_b32_e32 v176, 16, v242
	v_and_b32_e32 v177, 0xffff0000, v242
	v_lshlrev_b32_e32 v178, 16, v243
	v_and_b32_e32 v179, 0xffff0000, v243
	v_pk_mul_f32 v[20:21], v[20:21], v[134:135] op_sel_hi:[1,0]
	v_pk_mul_f32 v[22:23], v[22:23], v[134:135] op_sel_hi:[1,0]
	v_pk_mul_f32 v[24:25], v[24:25], v[134:135] op_sel_hi:[1,0]
	v_pk_mul_f32 v[26:27], v[26:27], v[134:135] op_sel_hi:[1,0]
	v_pk_fma_f32 v[172:173], v[20:21], v[156:157], v[172:173]
	v_pk_fma_f32 v[174:175], v[22:23], v[158:159], v[174:175]
	v_pk_fma_f32 v[176:177], v[24:25], v[160:161], v[176:177]
	v_pk_fma_f32 v[178:179], v[26:27], v[162:163], v[178:179]
	v_fmac_f32_e32 v145, v172, v172
	v_fmac_f32_e32 v145, v173, v173
	v_fmac_f32_e32 v145, v174, v174
	v_fmac_f32_e32 v145, v175, v175
	v_fmac_f32_e32 v145, v176, v176
	v_fmac_f32_e32 v145, v177, v177
	v_fmac_f32_e32 v145, v178, v178
	v_fmac_f32_e32 v145, v179, v179
	v_cvt_pk_bf16_f32 v184, v172, v173
	v_cvt_pk_bf16_f32 v185, v174, v175
	v_cvt_pk_bf16_f32 v186, v176, v177
	v_cvt_pk_bf16_f32 v187, v178, v179
	global_store_dwordx4 v140, v[184:187], s[22:23] offset:256
	s_add_u32 s22, s64, 0x58000
	s_addc_u32 s23, s65, 0
	v_lshlrev_b32_e32 v164, 16, v244
	v_and_b32_e32 v165, 0xffff0000, v244
	v_lshlrev_b32_e32 v166, 16, v245
	v_and_b32_e32 v167, 0xffff0000, v245
	v_lshlrev_b32_e32 v168, 16, v246
	v_and_b32_e32 v169, 0xffff0000, v246
	v_lshlrev_b32_e32 v170, 16, v247
	v_and_b32_e32 v171, 0xffff0000, v247
	v_pk_mul_f32 v[12:13], v[12:13], v[134:135] op_sel:[0,1] op_sel_hi:[1,1]
	v_pk_mul_f32 v[14:15], v[14:15], v[134:135] op_sel:[0,1] op_sel_hi:[1,1]
	v_pk_mul_f32 v[0:1], v[0:1], v[134:135] op_sel:[0,1] op_sel_hi:[1,1]
	v_pk_mul_f32 v[2:3], v[2:3], v[134:135] op_sel:[0,1] op_sel_hi:[1,1]
	v_pk_fma_f32 v[164:165], v[12:13], v[148:149], v[164:165]
	v_pk_fma_f32 v[166:167], v[14:15], v[150:151], v[166:167]
	v_pk_fma_f32 v[168:169], v[0:1], v[152:153], v[168:169]
	v_pk_fma_f32 v[170:171], v[2:3], v[154:155], v[170:171]
	v_mul_f32_e32 v146, v164, v164
	v_fmac_f32_e32 v146, v165, v165
	v_fmac_f32_e32 v146, v166, v166
	v_fmac_f32_e32 v146, v167, v167
	v_fmac_f32_e32 v146, v168, v168
	v_fmac_f32_e32 v146, v169, v169
	v_fmac_f32_e32 v146, v170, v170
	v_fmac_f32_e32 v146, v171, v171
	v_cvt_pk_bf16_f32 v180, v164, v165
	v_cvt_pk_bf16_f32 v181, v166, v167
	v_cvt_pk_bf16_f32 v182, v168, v169
	v_cvt_pk_bf16_f32 v183, v170, v171
	global_store_dwordx4 v140, v[180:183], s[22:23]
	v_lshlrev_b32_e32 v172, 16, v248
	v_and_b32_e32 v173, 0xffff0000, v248
	v_lshlrev_b32_e32 v174, 16, v249
	v_and_b32_e32 v175, 0xffff0000, v249
	v_lshlrev_b32_e32 v176, 16, v250
	v_and_b32_e32 v177, 0xffff0000, v250
	v_lshlrev_b32_e32 v178, 16, v251
	v_and_b32_e32 v179, 0xffff0000, v251
	v_pk_mul_f32 v[4:5], v[4:5], v[134:135] op_sel:[0,1] op_sel_hi:[1,1]
	v_pk_mul_f32 v[6:7], v[6:7], v[134:135] op_sel:[0,1] op_sel_hi:[1,1]
	v_pk_mul_f32 v[8:9], v[8:9], v[134:135] op_sel:[0,1] op_sel_hi:[1,1]
	v_pk_mul_f32 v[10:11], v[10:11], v[134:135] op_sel:[0,1] op_sel_hi:[1,1]
	v_pk_fma_f32 v[172:173], v[4:5], v[156:157], v[172:173]
	v_pk_fma_f32 v[174:175], v[6:7], v[158:159], v[174:175]
	v_pk_fma_f32 v[176:177], v[8:9], v[160:161], v[176:177]
	v_pk_fma_f32 v[178:179], v[10:11], v[162:163], v[178:179]
	v_fmac_f32_e32 v146, v172, v172
	v_fmac_f32_e32 v146, v173, v173
	v_fmac_f32_e32 v146, v174, v174
	v_fmac_f32_e32 v146, v175, v175
	v_fmac_f32_e32 v146, v176, v176
	v_fmac_f32_e32 v146, v177, v177
	v_fmac_f32_e32 v146, v178, v178
	v_fmac_f32_e32 v146, v179, v179
	v_cvt_pk_bf16_f32 v184, v172, v173
	v_cvt_pk_bf16_f32 v185, v174, v175
	v_cvt_pk_bf16_f32 v186, v176, v177
	v_cvt_pk_bf16_f32 v187, v178, v179
	global_store_dwordx4 v140, v[184:187], s[22:23] offset:256
	v_mov_b32_e32 v148, v138
	v_mov_b32_e32 v149, v139
	v_mov_b32_e32 v150, v141
	v_mov_b32_e32 v151, v142
	v_mov_b32_e32 v152, v143
	v_mov_b32_e32 v153, v144
	v_mov_b32_e32 v154, v145
	v_mov_b32_e32 v155, v146
	v_xor_b32_e32 v138, 16, v137
	v_xor_b32_e32 v139, 32, v137
	v_lshlrev_b32_e32 v138, 2, v138
	v_lshlrev_b32_e32 v139, 2, v139
	ds_bpermute_b32 v164, v138, v148
	ds_bpermute_b32 v165, v138, v149
	ds_bpermute_b32 v166, v138, v150
	ds_bpermute_b32 v167, v138, v151
	ds_bpermute_b32 v168, v138, v152
	ds_bpermute_b32 v169, v138, v153
	ds_bpermute_b32 v170, v138, v154
	ds_bpermute_b32 v171, v138, v155
	s_waitcnt lgkmcnt(0)
	v_add_f32_e32 v148, v148, v164
	v_add_f32_e32 v149, v149, v165
	v_add_f32_e32 v150, v150, v166
	v_add_f32_e32 v151, v151, v167
	v_add_f32_e32 v152, v152, v168
	v_add_f32_e32 v153, v153, v169
	v_add_f32_e32 v154, v154, v170
	v_add_f32_e32 v155, v155, v171
	ds_bpermute_b32 v164, v139, v148
	ds_bpermute_b32 v165, v139, v149
	ds_bpermute_b32 v166, v139, v150
	ds_bpermute_b32 v167, v139, v151
	ds_bpermute_b32 v168, v139, v152
	ds_bpermute_b32 v169, v139, v153
	ds_bpermute_b32 v170, v139, v154
	ds_bpermute_b32 v171, v139, v155
	s_waitcnt lgkmcnt(0)
	v_add_f32_e32 v148, v148, v164
	v_add_f32_e32 v149, v149, v165
	v_add_f32_e32 v150, v150, v166
	v_add_f32_e32 v151, v151, v167
	v_add_f32_e32 v152, v152, v168
	v_add_f32_e32 v153, v153, v169
	v_add_f32_e32 v154, v154, v170
	v_add_f32_e32 v155, v155, v171
	s_and_b32 s98, s2, 7
	s_lshl_b32 s98, s98, 3
	s_bfe_u32 s99, s2, 0x30003
	s_or_b32 s98, s98, s99
	s_lshr_b32 s99, s2, 6
	s_mul_i32 s99, s99, 0x42000
	s_lshl_b32 s98, s98, 10
	s_add_u32 s100, s62, s99
	s_addc_u32 s101, s63, 0
	s_add_u32 s100, s100, s98
	s_addc_u32 s101, s101, 0
	v_lshrrev_b32_e32 v158, 8, v136
	v_bfe_u32 v159, v136, 6, 2
	v_and_b32_e32 v160, 15, v136
	v_lshl_add_u32 v160, v158, 6, v160
	v_mul_u32_u24_e32 v159, 0x4200, v159
	v_add_u32_e32 v160, v160, v159
	v_lshlrev_b32_e32 v160, 2, v160
	v_bfe_u32 v161, v136, 4, 2
	v_cmp_eq_u32_e32 vcc, 0, v161
	s_and_saveexec_b64 s[0:1], vcc
	global_store_dword v160, v148, s[100:101]
	global_store_dword v160, v149, s[100:101] offset:64
	global_store_dword v160, v150, s[100:101] offset:128
	global_store_dword v160, v151, s[100:101] offset:192
	global_store_dword v160, v152, s[100:101] offset:512
	global_store_dword v160, v153, s[100:101] offset:576
	global_store_dword v160, v154, s[100:101] offset:640
	global_store_dword v160, v155, s[100:101] offset:704
	s_or_b64 exec, exec, s[0:1]
	v_bfe_u32 v183, v136, 1, 2
	v_lshrrev_b32_e32 v187, 6, v136
	v_lshlrev_b32_e32 v190, 11, v136
	v_lshrrev_b32_e32 v252, 1, v136
	v_and_b32_e32 v132, 48, v136
	v_and_b32_e32 v189, 63, v136
	v_lshrrev_b32_e32 v182, 3, v136
	v_lshlrev_b32_e32 v188, 2, v136
	v_lshl_add_u32 v186, v183, 6, 0
	v_and_b32_e32 v191, 15, v136
	v_cndmask_b32_e64 v1, 0, 1, s[8:9]
	v_mov_b32_e32 v0, v136
	v_cmp_ne_u32_e64 s[6:7], 1, v1
	s_andn2_b64 vcc, exec, s[8:9]
	s_cbranch_vccnz .LBB0_1254
	v_and_b32_e32 v4, 63, v0
	v_ashrrev_i32_e32 v0, 5, v0
	v_readlane_b32 s8, v253, 3
	v_and_b32_e32 v5, -2, v0
	v_lshlrev_b32_e32 v0, 4, v4
	v_mov_b32_e32 v1, 0
	v_readlane_b32 s9, v253, 4
	s_mov_b64 s[0:1], 0x3000
	v_readlane_b32 s12, v253, 7
	v_lshl_add_u64 v[2:3], s[8:9], 0, v[0:1]
	v_lshl_add_u64 v[16:17], v[2:3], 0, s[0:1]
	v_and_b32_e32 v2, 64, v137
	v_add_u32_e32 v2, 64, v2
	v_xor_b32_e32 v3, 32, v137
	v_cmp_lt_i32_e64 s[0:1], v3, v2
	v_mul_u32_u24_e32 v0, 0x4200, v4
	v_lshlrev_b32_e32 v0, 2, v0
	v_cndmask_b32_e64 v3, v137, v3, s[0:1]
	v_lshlrev_b32_e32 v50, 2, v3
	v_xor_b32_e32 v3, 16, v137
	v_cmp_lt_i32_e64 s[0:1], v3, v2
	v_readlane_b32 s13, v253, 8
	v_lshl_add_u64 v[18:19], s[44:45], 0, v[0:1]
	v_cndmask_b32_e64 v3, v137, v3, s[0:1]
	v_lshlrev_b32_e32 v51, 2, v3
	v_xor_b32_e32 v3, 8, v137
	v_cmp_lt_i32_e64 s[0:1], v3, v2
	v_lshlrev_b32_e32 v0, 3, v4
	v_cmp_gt_u32_e32 vcc, 16, v4
	v_cndmask_b32_e64 v3, v137, v3, s[0:1]
	v_lshlrev_b32_e32 v52, 2, v3
	v_xor_b32_e32 v3, 4, v137
	v_cmp_lt_i32_e64 s[0:1], v3, v2
	v_lshl_add_u64 v[20:21], s[64:65], 0, v[0:1]
	v_lshl_add_u64 v[22:23], s[60:61], 0, v[0:1]
	v_cndmask_b32_e64 v3, v137, v3, s[0:1]
	v_lshlrev_b32_e32 v53, 2, v3
	v_xor_b32_e32 v3, 2, v137
	v_cmp_lt_i32_e64 s[0:1], v3, v2
	v_lshl_add_u64 v[24:25], s[58:59], 0, v[0:1]
	v_lshl_add_u32 v26, s2, 4, v5
	v_cndmask_b32_e64 v3, v137, v3, s[0:1]
	v_lshlrev_b32_e32 v54, 2, v3
	v_xor_b32_e32 v3, 1, v137
	v_cmp_lt_i32_e64 s[0:1], v3, v2
	s_lshl_b32 s3, s38, 4
	v_mov_b32_e32 v56, 0x358637bd
	v_cndmask_b32_e64 v2, v137, v3, s[0:1]
	v_lshlrev_b32_e32 v55, 2, v2
	v_cmp_eq_u32_e64 s[0:1], 0, v4
	s_mov_b32 s12, 0x800000
	s_mov_b32 s13, s2
	v_readlane_b32 s10, v253, 5
	v_readlane_b32 s11, v253, 6
	v_readlane_b32 s14, v253, 9
	v_readlane_b32 s15, v253, 10
	v_readlane_b32 s16, v253, 11
	v_readlane_b32 s17, v253, 12
	v_readlane_b32 s18, v253, 13
	v_readlane_b32 s19, v253, 14
	v_readlane_b32 s20, v253, 15
	v_readlane_b32 s21, v253, 16
	v_readlane_b32 s22, v253, 17
	v_readlane_b32 s23, v253, 18
	s_addk_i32 s13, 0x400
	v_add_u32_e32 v26, 0x4000, v26
	s_cmpk_lt_i32 s13, 0x420
	s_cbranch_scc0 .LBB0_1254
	s_branch .LBB0_1246

.LBB0_1468:
	s_or_b64 exec, exec, s[0:1]
	s_and_b64 vcc, exec, s[6:7]
	s_waitcnt lgkmcnt(0)
	s_barrier
	s_and_b32 s99, s2, 7
	s_lshl_b32 s99, s99, 3
	s_bfe_u32 s100, s2, 0x30003
	s_or_b32 s99, s99, s100
	s_lshr_b32 s100, s2, 6
	v_and_b32_e32 v172, 0xff, v136
	v_lshrrev_b32_e32 v173, 8, v136
	v_mul_u32_u24_e32 v173, 0x84000, v173
	v_lshl_add_u32 v172, v172, 2, v173
	s_lshl_b32 s24, s99, 10
	s_add_u32 s18, s44, s24
	s_addc_u32 s19, s45, 0
	global_load_dword v164, v172, s[18:19]
	s_add_u32 s18, s18, 0x10800
	s_addc_u32 s19, s19, 0
	global_load_dword v165, v172, s[18:19]
	s_add_u32 s18, s18, 0x10800
	s_addc_u32 s19, s19, 0
	global_load_dword v166, v172, s[18:19]
	s_add_u32 s18, s18, 0x10800
	s_addc_u32 s19, s19, 0
	global_load_dword v167, v172, s[18:19]
	s_add_u32 s18, s18, 0x10800
	s_addc_u32 s19, s19, 0
	global_load_dword v168, v172, s[18:19]
	s_add_u32 s18, s18, 0x10800
	s_addc_u32 s19, s19, 0
	global_load_dword v169, v172, s[18:19]
	s_add_u32 s18, s18, 0x10800
	s_addc_u32 s19, s19, 0
	global_load_dword v170, v172, s[18:19]
	s_add_u32 s18, s18, 0x10800
	s_addc_u32 s19, s19, 0
	global_load_dword v171, v172, s[18:19]
	v_lshrrev_b32_e32 v141, 8, v136
	v_and_b32_e32 v142, 15, v136
	v_lshl_add_u32 v141, v141, 6, v142
	v_bfe_u32 v144, v136, 6, 2
	v_bfe_u32 v145, v136, 4, 2
	v_lshlrev_b32_e32 v144, 5, v144
	v_lshl_add_u32 v144, v145, 3, v144
	s_lshl_b32 s24, s100, 8
	v_add_u32_e32 v144, s24, v144
	s_lshl_b32 s25, s99, 8
	v_add_u32_e32 v145, s25, v141
	v_lshl_add_u32 v146, v145, 10, v144
	v_lshlrev_b32_e32 v139, 1, v146
	v_lshlrev_b32_e32 v140, 2, v146
	v_lshlrev_b32_e32 v138, 2, v144
	v_readlane_b32 s18, v253, 3
	v_readlane_b32 s19, v253, 4
	v_readlane_b32 s20, v254, 52
	v_readlane_b32 s21, v254, 53
	s_nop 4
	s_add_u32 s18, s18, 0x5000
	s_addc_u32 s19, s19, 0
	global_load_dwordx4 v[148:151], v138, s[18:19]
	global_load_dwordx4 v[152:155], v138, s[18:19] offset:16
	global_load_dwordx4 v[156:159], v138, s[18:19] offset:512
	global_load_dwordx4 v[160:163], v138, s[18:19] offset:528
	s_add_u32 s22, s64, 0x0
	s_addc_u32 s23, s65, 0
	global_load_dwordx4 v[188:191], v139, s[22:23] nt
	global_load_dwordx4 v[192:195], v139, s[22:23] offset:256 nt
	s_add_u32 s22, s64, 0x8000
	s_addc_u32 s23, s65, 0
	global_load_dwordx4 v[196:199], v139, s[22:23] nt
	global_load_dwordx4 v[200:203], v139, s[22:23] offset:256 nt
	s_add_u32 s22, s64, 0x10000
	s_addc_u32 s23, s65, 0
	global_load_dwordx4 v[204:207], v139, s[22:23] nt
	global_load_dwordx4 v[208:211], v139, s[22:23] offset:256 nt
	s_add_u32 s22, s64, 0x18000
	s_addc_u32 s23, s65, 0
	global_load_dwordx4 v[212:215], v139, s[22:23] nt
	global_load_dwordx4 v[216:219], v139, s[22:23] offset:256 nt
	s_add_u32 s22, s64, 0x40000
	s_addc_u32 s23, s65, 0
	global_load_dwordx4 v[220:223], v139, s[22:23] nt
	global_load_dwordx4 v[224:227], v139, s[22:23] offset:256 nt
	s_add_u32 s22, s64, 0x48000
	s_addc_u32 s23, s65, 0
	global_load_dwordx4 v[228:231], v139, s[22:23] nt
	global_load_dwordx4 v[232:235], v139, s[22:23] offset:256 nt
	s_add_u32 s22, s64, 0x50000
	s_addc_u32 s23, s65, 0
	global_load_dwordx4 v[236:239], v139, s[22:23] nt
	global_load_dwordx4 v[240:243], v139, s[22:23] offset:256 nt
	s_add_u32 s22, s64, 0x58000
	s_addc_u32 s23, s65, 0
	global_load_dwordx4 v[244:247], v139, s[22:23] nt
	global_load_dwordx4 v[248:251], v139, s[22:23] offset:256 nt
	s_waitcnt vmcnt(20)
	v_add_f32_e32 v164, v164, v165
	v_add_f32_e32 v164, v164, v166
	v_add_f32_e32 v164, v164, v167
	v_add_f32_e32 v164, v164, v168
	v_add_f32_e32 v164, v164, v169
	v_add_f32_e32 v164, v164, v170
	v_add_f32_e32 v164, v164, v171
	v_lshlrev_b32_e32 v173, 2, v136
	ds_write_b32 v173, v164
	s_waitcnt lgkmcnt(0)
	s_barrier
	v_lshlrev_b32_e32 v142, 2, v141
	ds_read_b32 v128, v142 offset:0
	ds_read_b32 v174, v142 offset:1024
	ds_read_b32 v129, v142 offset:64
	ds_read_b32 v175, v142 offset:1088
	ds_read_b32 v130, v142 offset:128
	ds_read_b32 v176, v142 offset:1152
	ds_read_b32 v131, v142 offset:192
	ds_read_b32 v177, v142 offset:1216
	ds_read_b32 v132, v142 offset:512
	ds_read_b32 v178, v142 offset:1536
	ds_read_b32 v133, v142 offset:576
	ds_read_b32 v179, v142 offset:1600
	ds_read_b32 v134, v142 offset:640
	ds_read_b32 v180, v142 offset:1664
	ds_read_b32 v135, v142 offset:704
	ds_read_b32 v181, v142 offset:1728
	s_waitcnt lgkmcnt(0)
	s_mov_b32 s101, 0x3a800000
	v_mov_b32_e32 v143, 0x358637bd
	v_add_f32_e32 v128, v128, v174
	v_add_f32_e32 v129, v129, v175
	v_add_f32_e32 v130, v130, v176
	v_add_f32_e32 v131, v131, v177
	v_add_f32_e32 v132, v132, v178
	v_add_f32_e32 v133, v133, v179
	v_add_f32_e32 v134, v134, v180
	v_add_f32_e32 v135, v135, v181
	v_fma_f32 v128, v128, s101, v143
	v_fma_f32 v129, v129, s101, v143
	v_fma_f32 v130, v130, s101, v143
	v_fma_f32 v131, v131, s101, v143
	v_fma_f32 v132, v132, s101, v143
	v_fma_f32 v133, v133, s101, v143
	v_fma_f32 v134, v134, s101, v143
	v_fma_f32 v135, v135, s101, v143
	v_rsq_f32_e32 v128, v128
	v_rsq_f32_e32 v129, v129
	v_rsq_f32_e32 v130, v130
	v_rsq_f32_e32 v131, v131
	v_rsq_f32_e32 v132, v132
	v_rsq_f32_e32 v133, v133
	v_rsq_f32_e32 v134, v134
	v_rsq_f32_e32 v135, v135
	s_waitcnt vmcnt(0)
	s_add_u32 s22, s20, 0x0
	s_addc_u32 s23, s21, 0
	v_lshlrev_b32_e32 v164, 16, v188
	v_and_b32_e32 v165, 0xffff0000, v188
	v_lshlrev_b32_e32 v166, 16, v189
	v_and_b32_e32 v167, 0xffff0000, v189
	v_lshlrev_b32_e32 v168, 16, v190
	v_and_b32_e32 v169, 0xffff0000, v190
	v_lshlrev_b32_e32 v170, 16, v191
	v_and_b32_e32 v171, 0xffff0000, v191
	v_pk_mul_f32 v[124:125], v[124:125], v[128:129] op_sel_hi:[1,0]
	v_pk_mul_f32 v[126:127], v[126:127], v[128:129] op_sel_hi:[1,0]
	v_pk_mul_f32 v[112:113], v[112:113], v[128:129] op_sel_hi:[1,0]
	v_pk_mul_f32 v[114:115], v[114:115], v[128:129] op_sel_hi:[1,0]
	v_pk_fma_f32 v[164:165], v[124:125], v[148:149], v[164:165]
	v_pk_fma_f32 v[166:167], v[126:127], v[150:151], v[166:167]
	v_pk_fma_f32 v[168:169], v[112:113], v[152:153], v[168:169]
	v_pk_fma_f32 v[170:171], v[114:115], v[154:155], v[170:171]
	global_store_dwordx4 v140, v[164:167], s[22:23]
	global_store_dwordx4 v140, v[168:171], s[22:23] offset:16
	v_lshlrev_b32_e32 v172, 16, v192
	v_and_b32_e32 v173, 0xffff0000, v192
	v_lshlrev_b32_e32 v174, 16, v193
	v_and_b32_e32 v175, 0xffff0000, v193
	v_lshlrev_b32_e32 v176, 16, v194
	v_and_b32_e32 v177, 0xffff0000, v194
	v_lshlrev_b32_e32 v178, 16, v195
	v_and_b32_e32 v179, 0xffff0000, v195
	v_pk_mul_f32 v[120:121], v[120:121], v[128:129] op_sel_hi:[1,0]
	v_pk_mul_f32 v[122:123], v[122:123], v[128:129] op_sel_hi:[1,0]
	v_pk_mul_f32 v[116:117], v[116:117], v[128:129] op_sel_hi:[1,0]
	v_pk_mul_f32 v[118:119], v[118:119], v[128:129] op_sel_hi:[1,0]
	v_pk_fma_f32 v[172:173], v[120:121], v[156:157], v[172:173]
	v_pk_fma_f32 v[174:175], v[122:123], v[158:159], v[174:175]
	v_pk_fma_f32 v[176:177], v[116:117], v[160:161], v[176:177]
	v_pk_fma_f32 v[178:179], v[118:119], v[162:163], v[178:179]
	global_store_dwordx4 v140, v[172:175], s[22:23] offset:512
	global_store_dwordx4 v140, v[176:179], s[22:23] offset:528
	s_add_u32 s22, s20, 0x10000
	s_addc_u32 s23, s21, 0
	v_lshlrev_b32_e32 v180, 16, v196
	v_and_b32_e32 v181, 0xffff0000, v196
	v_lshlrev_b32_e32 v182, 16, v197
	v_and_b32_e32 v183, 0xffff0000, v197
	v_lshlrev_b32_e32 v184, 16, v198
	v_and_b32_e32 v185, 0xffff0000, v198
	v_lshlrev_b32_e32 v186, 16, v199
	v_and_b32_e32 v187, 0xffff0000, v199
	v_pk_mul_f32 v[108:109], v[108:109], v[128:129] op_sel:[0,1] op_sel_hi:[1,1]
	v_pk_mul_f32 v[110:111], v[110:111], v[128:129] op_sel:[0,1] op_sel_hi:[1,1]
	v_pk_mul_f32 v[96:97], v[96:97], v[128:129] op_sel:[0,1] op_sel_hi:[1,1]
	v_pk_mul_f32 v[98:99], v[98:99], v[128:129] op_sel:[0,1] op_sel_hi:[1,1]
	v_pk_fma_f32 v[180:181], v[108:109], v[148:149], v[180:181]
	v_pk_fma_f32 v[182:183], v[110:111], v[150:151], v[182:183]
	v_pk_fma_f32 v[184:185], v[96:97], v[152:153], v[184:185]
	v_pk_fma_f32 v[186:187], v[98:99], v[154:155], v[186:187]
	global_store_dwordx4 v140, v[180:183], s[22:23]
	global_store_dwordx4 v140, v[184:187], s[22:23] offset:16
	v_lshlrev_b32_e32 v164, 16, v200
	v_and_b32_e32 v165, 0xffff0000, v200
	v_lshlrev_b32_e32 v166, 16, v201
	v_and_b32_e32 v167, 0xffff0000, v201
	v_lshlrev_b32_e32 v168, 16, v202
	v_and_b32_e32 v169, 0xffff0000, v202
	v_lshlrev_b32_e32 v170, 16, v203
	v_and_b32_e32 v171, 0xffff0000, v203
	v_pk_mul_f32 v[100:101], v[100:101], v[128:129] op_sel:[0,1] op_sel_hi:[1,1]
	v_pk_mul_f32 v[102:103], v[102:103], v[128:129] op_sel:[0,1] op_sel_hi:[1,1]
	v_pk_mul_f32 v[104:105], v[104:105], v[128:129] op_sel:[0,1] op_sel_hi:[1,1]
	v_pk_mul_f32 v[106:107], v[106:107], v[128:129] op_sel:[0,1] op_sel_hi:[1,1]
	v_pk_fma_f32 v[164:165], v[100:101], v[156:157], v[164:165]
	v_pk_fma_f32 v[166:167], v[102:103], v[158:159], v[166:167]
	v_pk_fma_f32 v[168:169], v[104:105], v[160:161], v[168:169]
	v_pk_fma_f32 v[170:171], v[106:107], v[162:163], v[170:171]
	global_store_dwordx4 v140, v[164:167], s[22:23] offset:512
	global_store_dwordx4 v140, v[168:171], s[22:23] offset:528
	s_add_u32 s22, s20, 0x20000
	s_addc_u32 s23, s21, 0
	v_lshlrev_b32_e32 v172, 16, v204
	v_and_b32_e32 v173, 0xffff0000, v204
	v_lshlrev_b32_e32 v174, 16, v205
	v_and_b32_e32 v175, 0xffff0000, v205
	v_lshlrev_b32_e32 v176, 16, v206
	v_and_b32_e32 v177, 0xffff0000, v206
	v_lshlrev_b32_e32 v178, 16, v207
	v_and_b32_e32 v179, 0xffff0000, v207
	v_pk_mul_f32 v[92:93], v[92:93], v[130:131] op_sel_hi:[1,0]
	v_pk_mul_f32 v[94:95], v[94:95], v[130:131] op_sel_hi:[1,0]
	v_pk_mul_f32 v[80:81], v[80:81], v[130:131] op_sel_hi:[1,0]
	v_pk_mul_f32 v[82:83], v[82:83], v[130:131] op_sel_hi:[1,0]
	v_pk_fma_f32 v[172:173], v[92:93], v[148:149], v[172:173]
	v_pk_fma_f32 v[174:175], v[94:95], v[150:151], v[174:175]
	v_pk_fma_f32 v[176:177], v[80:81], v[152:153], v[176:177]
	v_pk_fma_f32 v[178:179], v[82:83], v[154:155], v[178:179]
	global_store_dwordx4 v140, v[172:175], s[22:23]
	global_store_dwordx4 v140, v[176:179], s[22:23] offset:16
	v_lshlrev_b32_e32 v180, 16, v208
	v_and_b32_e32 v181, 0xffff0000, v208
	v_lshlrev_b32_e32 v182, 16, v209
	v_and_b32_e32 v183, 0xffff0000, v209
	v_lshlrev_b32_e32 v184, 16, v210
	v_and_b32_e32 v185, 0xffff0000, v210
	v_lshlrev_b32_e32 v186, 16, v211
	v_and_b32_e32 v187, 0xffff0000, v211
	v_pk_mul_f32 v[84:85], v[84:85], v[130:131] op_sel_hi:[1,0]
	v_pk_mul_f32 v[86:87], v[86:87], v[130:131] op_sel_hi:[1,0]
	v_pk_mul_f32 v[88:89], v[88:89], v[130:131] op_sel_hi:[1,0]
	v_pk_mul_f32 v[90:91], v[90:91], v[130:131] op_sel_hi:[1,0]
	v_pk_fma_f32 v[180:181], v[84:85], v[156:157], v[180:181]
	v_pk_fma_f32 v[182:183], v[86:87], v[158:159], v[182:183]
	v_pk_fma_f32 v[184:185], v[88:89], v[160:161], v[184:185]
	v_pk_fma_f32 v[186:187], v[90:91], v[162:163], v[186:187]
	global_store_dwordx4 v140, v[180:183], s[22:23] offset:512
	global_store_dwordx4 v140, v[184:187], s[22:23] offset:528
	s_add_u32 s22, s20, 0x30000
	s_addc_u32 s23, s21, 0
	v_lshlrev_b32_e32 v164, 16, v212
	v_and_b32_e32 v165, 0xffff0000, v212
	v_lshlrev_b32_e32 v166, 16, v213
	v_and_b32_e32 v167, 0xffff0000, v213
	v_lshlrev_b32_e32 v168, 16, v214
	v_and_b32_e32 v169, 0xffff0000, v214
	v_lshlrev_b32_e32 v170, 16, v215
	v_and_b32_e32 v171, 0xffff0000, v215
	v_pk_mul_f32 v[76:77], v[76:77], v[130:131] op_sel:[0,1] op_sel_hi:[1,1]
	v_pk_mul_f32 v[78:79], v[78:79], v[130:131] op_sel:[0,1] op_sel_hi:[1,1]
	v_pk_mul_f32 v[64:65], v[64:65], v[130:131] op_sel:[0,1] op_sel_hi:[1,1]
	v_pk_mul_f32 v[66:67], v[66:67], v[130:131] op_sel:[0,1] op_sel_hi:[1,1]
	v_pk_fma_f32 v[164:165], v[76:77], v[148:149], v[164:165]
	v_pk_fma_f32 v[166:167], v[78:79], v[150:151], v[166:167]
	v_pk_fma_f32 v[168:169], v[64:65], v[152:153], v[168:169]
	v_pk_fma_f32 v[170:171], v[66:67], v[154:155], v[170:171]
	global_store_dwordx4 v140, v[164:167], s[22:23]
	global_store_dwordx4 v140, v[168:171], s[22:23] offset:16
	v_lshlrev_b32_e32 v172, 16, v216
	v_and_b32_e32 v173, 0xffff0000, v216
	v_lshlrev_b32_e32 v174, 16, v217
	v_and_b32_e32 v175, 0xffff0000, v217
	v_lshlrev_b32_e32 v176, 16, v218
	v_and_b32_e32 v177, 0xffff0000, v218
	v_lshlrev_b32_e32 v178, 16, v219
	v_and_b32_e32 v179, 0xffff0000, v219
	v_pk_mul_f32 v[68:69], v[68:69], v[130:131] op_sel:[0,1] op_sel_hi:[1,1]
	v_pk_mul_f32 v[70:71], v[70:71], v[130:131] op_sel:[0,1] op_sel_hi:[1,1]
	v_pk_mul_f32 v[72:73], v[72:73], v[130:131] op_sel:[0,1] op_sel_hi:[1,1]
	v_pk_mul_f32 v[74:75], v[74:75], v[130:131] op_sel:[0,1] op_sel_hi:[1,1]
	v_pk_fma_f32 v[172:173], v[68:69], v[156:157], v[172:173]
	v_pk_fma_f32 v[174:175], v[70:71], v[158:159], v[174:175]
	v_pk_fma_f32 v[176:177], v[72:73], v[160:161], v[176:177]
	v_pk_fma_f32 v[178:179], v[74:75], v[162:163], v[178:179]
	global_store_dwordx4 v140, v[172:175], s[22:23] offset:512
	global_store_dwordx4 v140, v[176:179], s[22:23] offset:528
	s_add_u32 s22, s20, 0x80000
	s_addc_u32 s23, s21, 0
	v_lshlrev_b32_e32 v180, 16, v220
	v_and_b32_e32 v181, 0xffff0000, v220
	v_lshlrev_b32_e32 v182, 16, v221
	v_and_b32_e32 v183, 0xffff0000, v221
	v_lshlrev_b32_e32 v184, 16, v222
	v_and_b32_e32 v185, 0xffff0000, v222
	v_lshlrev_b32_e32 v186, 16, v223
	v_and_b32_e32 v187, 0xffff0000, v223
	v_pk_mul_f32 v[60:61], v[60:61], v[132:133] op_sel_hi:[1,0]
	v_pk_mul_f32 v[62:63], v[62:63], v[132:133] op_sel_hi:[1,0]
	v_pk_mul_f32 v[48:49], v[48:49], v[132:133] op_sel_hi:[1,0]
	v_pk_mul_f32 v[50:51], v[50:51], v[132:133] op_sel_hi:[1,0]
	v_pk_fma_f32 v[180:181], v[60:61], v[148:149], v[180:181]
	v_pk_fma_f32 v[182:183], v[62:63], v[150:151], v[182:183]
	v_pk_fma_f32 v[184:185], v[48:49], v[152:153], v[184:185]
	v_pk_fma_f32 v[186:187], v[50:51], v[154:155], v[186:187]
	global_store_dwordx4 v140, v[180:183], s[22:23]
	global_store_dwordx4 v140, v[184:187], s[22:23] offset:16
	v_lshlrev_b32_e32 v164, 16, v224
	v_and_b32_e32 v165, 0xffff0000, v224
	v_lshlrev_b32_e32 v166, 16, v225
	v_and_b32_e32 v167, 0xffff0000, v225
	v_lshlrev_b32_e32 v168, 16, v226
	v_and_b32_e32 v169, 0xffff0000, v226
	v_lshlrev_b32_e32 v170, 16, v227
	v_and_b32_e32 v171, 0xffff0000, v227
	v_pk_mul_f32 v[52:53], v[52:53], v[132:133] op_sel_hi:[1,0]
	v_pk_mul_f32 v[54:55], v[54:55], v[132:133] op_sel_hi:[1,0]
	v_pk_mul_f32 v[56:57], v[56:57], v[132:133] op_sel_hi:[1,0]
	v_pk_mul_f32 v[58:59], v[58:59], v[132:133] op_sel_hi:[1,0]
	v_pk_fma_f32 v[164:165], v[52:53], v[156:157], v[164:165]
	v_pk_fma_f32 v[166:167], v[54:55], v[158:159], v[166:167]
	v_pk_fma_f32 v[168:169], v[56:57], v[160:161], v[168:169]
	v_pk_fma_f32 v[170:171], v[58:59], v[162:163], v[170:171]
	global_store_dwordx4 v140, v[164:167], s[22:23] offset:512
	global_store_dwordx4 v140, v[168:171], s[22:23] offset:528
	s_add_u32 s22, s20, 0x90000
	s_addc_u32 s23, s21, 0
	v_lshlrev_b32_e32 v172, 16, v228
	v_and_b32_e32 v173, 0xffff0000, v228
	v_lshlrev_b32_e32 v174, 16, v229
	v_and_b32_e32 v175, 0xffff0000, v229
	v_lshlrev_b32_e32 v176, 16, v230
	v_and_b32_e32 v177, 0xffff0000, v230
	v_lshlrev_b32_e32 v178, 16, v231
	v_and_b32_e32 v179, 0xffff0000, v231
	v_pk_mul_f32 v[44:45], v[44:45], v[132:133] op_sel:[0,1] op_sel_hi:[1,1]
	v_pk_mul_f32 v[46:47], v[46:47], v[132:133] op_sel:[0,1] op_sel_hi:[1,1]
	v_pk_mul_f32 v[32:33], v[32:33], v[132:133] op_sel:[0,1] op_sel_hi:[1,1]
	v_pk_mul_f32 v[34:35], v[34:35], v[132:133] op_sel:[0,1] op_sel_hi:[1,1]
	v_pk_fma_f32 v[172:173], v[44:45], v[148:149], v[172:173]
	v_pk_fma_f32 v[174:175], v[46:47], v[150:151], v[174:175]
	v_pk_fma_f32 v[176:177], v[32:33], v[152:153], v[176:177]
	v_pk_fma_f32 v[178:179], v[34:35], v[154:155], v[178:179]
	global_store_dwordx4 v140, v[172:175], s[22:23]
	global_store_dwordx4 v140, v[176:179], s[22:23] offset:16
	v_lshlrev_b32_e32 v180, 16, v232
	v_and_b32_e32 v181, 0xffff0000, v232
	v_lshlrev_b32_e32 v182, 16, v233
	v_and_b32_e32 v183, 0xffff0000, v233
	v_lshlrev_b32_e32 v184, 16, v234
	v_and_b32_e32 v185, 0xffff0000, v234
	v_lshlrev_b32_e32 v186, 16, v235
	v_and_b32_e32 v187, 0xffff0000, v235
	v_pk_mul_f32 v[36:37], v[36:37], v[132:133] op_sel:[0,1] op_sel_hi:[1,1]
	v_pk_mul_f32 v[38:39], v[38:39], v[132:133] op_sel:[0,1] op_sel_hi:[1,1]
	v_pk_mul_f32 v[40:41], v[40:41], v[132:133] op_sel:[0,1] op_sel_hi:[1,1]
	v_pk_mul_f32 v[42:43], v[42:43], v[132:133] op_sel:[0,1] op_sel_hi:[1,1]
	v_pk_fma_f32 v[180:181], v[36:37], v[156:157], v[180:181]
	v_pk_fma_f32 v[182:183], v[38:39], v[158:159], v[182:183]
	v_pk_fma_f32 v[184:185], v[40:41], v[160:161], v[184:185]
	v_pk_fma_f32 v[186:187], v[42:43], v[162:163], v[186:187]
	global_store_dwordx4 v140, v[180:183], s[22:23] offset:512
	global_store_dwordx4 v140, v[184:187], s[22:23] offset:528
	s_add_u32 s22, s20, 0xa0000
	s_addc_u32 s23, s21, 0
	v_lshlrev_b32_e32 v164, 16, v236
	v_and_b32_e32 v165, 0xffff0000, v236
	v_lshlrev_b32_e32 v166, 16, v237
	v_and_b32_e32 v167, 0xffff0000, v237
	v_lshlrev_b32_e32 v168, 16, v238
	v_and_b32_e32 v169, 0xffff0000, v238
	v_lshlrev_b32_e32 v170, 16, v239
	v_and_b32_e32 v171, 0xffff0000, v239
	v_pk_mul_f32 v[28:29], v[28:29], v[134:135] op_sel_hi:[1,0]
	v_pk_mul_f32 v[30:31], v[30:31], v[134:135] op_sel_hi:[1,0]
	v_pk_mul_f32 v[16:17], v[16:17], v[134:135] op_sel_hi:[1,0]
	v_pk_mul_f32 v[18:19], v[18:19], v[134:135] op_sel_hi:[1,0]
	v_pk_fma_f32 v[164:165], v[28:29], v[148:149], v[164:165]
	v_pk_fma_f32 v[166:167], v[30:31], v[150:151], v[166:167]
	v_pk_fma_f32 v[168:169], v[16:17], v[152:153], v[168:169]
	v_pk_fma_f32 v[170:171], v[18:19], v[154:155], v[170:171]
	global_store_dwordx4 v140, v[164:167], s[22:23]
	global_store_dwordx4 v140, v[168:171], s[22:23] offset:16
	v_lshlrev_b32_e32 v172, 16, v240
	v_and_b32_e32 v173, 0xffff0000, v240
	v_lshlrev_b32_e32 v174, 16, v241
	v_and_b32_e32 v175, 0xffff0000, v241
	v_lshlrev_b32_e32 v176, 16, v242
	v_and_b32_e32 v177, 0xffff0000, v242
	v_lshlrev_b32_e32 v178, 16, v243
	v_and_b32_e32 v179, 0xffff0000, v243
	v_pk_mul_f32 v[20:21], v[20:21], v[134:135] op_sel_hi:[1,0]
	v_pk_mul_f32 v[22:23], v[22:23], v[134:135] op_sel_hi:[1,0]
	v_pk_mul_f32 v[24:25], v[24:25], v[134:135] op_sel_hi:[1,0]
	v_pk_mul_f32 v[26:27], v[26:27], v[134:135] op_sel_hi:[1,0]
	v_pk_fma_f32 v[172:173], v[20:21], v[156:157], v[172:173]
	v_pk_fma_f32 v[174:175], v[22:23], v[158:159], v[174:175]
	v_pk_fma_f32 v[176:177], v[24:25], v[160:161], v[176:177]
	v_pk_fma_f32 v[178:179], v[26:27], v[162:163], v[178:179]
	global_store_dwordx4 v140, v[172:175], s[22:23] offset:512
	global_store_dwordx4 v140, v[176:179], s[22:23] offset:528
	s_add_u32 s22, s20, 0xb0000
	s_addc_u32 s23, s21, 0
	v_lshlrev_b32_e32 v180, 16, v244
	v_and_b32_e32 v181, 0xffff0000, v244
	v_lshlrev_b32_e32 v182, 16, v245
	v_and_b32_e32 v183, 0xffff0000, v245
	v_lshlrev_b32_e32 v184, 16, v246
	v_and_b32_e32 v185, 0xffff0000, v246
	v_lshlrev_b32_e32 v186, 16, v247
	v_and_b32_e32 v187, 0xffff0000, v247
	v_pk_mul_f32 v[12:13], v[12:13], v[134:135] op_sel:[0,1] op_sel_hi:[1,1]
	v_pk_mul_f32 v[14:15], v[14:15], v[134:135] op_sel:[0,1] op_sel_hi:[1,1]
	v_pk_mul_f32 v[0:1], v[0:1], v[134:135] op_sel:[0,1] op_sel_hi:[1,1]
	v_pk_mul_f32 v[2:3], v[2:3], v[134:135] op_sel:[0,1] op_sel_hi:[1,1]
	v_pk_fma_f32 v[180:181], v[12:13], v[148:149], v[180:181]
	v_pk_fma_f32 v[182:183], v[14:15], v[150:151], v[182:183]
	v_pk_fma_f32 v[184:185], v[0:1], v[152:153], v[184:185]
	v_pk_fma_f32 v[186:187], v[2:3], v[154:155], v[186:187]
	global_store_dwordx4 v140, v[180:183], s[22:23]
	global_store_dwordx4 v140, v[184:187], s[22:23] offset:16
	v_lshlrev_b32_e32 v164, 16, v248
	v_and_b32_e32 v165, 0xffff0000, v248
	v_lshlrev_b32_e32 v166, 16, v249
	v_and_b32_e32 v167, 0xffff0000, v249
	v_lshlrev_b32_e32 v168, 16, v250
	v_and_b32_e32 v169, 0xffff0000, v250
	v_lshlrev_b32_e32 v170, 16, v251
	v_and_b32_e32 v171, 0xffff0000, v251
	v_pk_mul_f32 v[4:5], v[4:5], v[134:135] op_sel:[0,1] op_sel_hi:[1,1]
	v_pk_mul_f32 v[6:7], v[6:7], v[134:135] op_sel:[0,1] op_sel_hi:[1,1]
	v_pk_mul_f32 v[8:9], v[8:9], v[134:135] op_sel:[0,1] op_sel_hi:[1,1]
	v_pk_mul_f32 v[10:11], v[10:11], v[134:135] op_sel:[0,1] op_sel_hi:[1,1]
	v_pk_fma_f32 v[164:165], v[4:5], v[156:157], v[164:165]
	v_pk_fma_f32 v[166:167], v[6:7], v[158:159], v[166:167]
	v_pk_fma_f32 v[168:169], v[8:9], v[160:161], v[168:169]
	v_pk_fma_f32 v[170:171], v[10:11], v[162:163], v[170:171]
	global_store_dwordx4 v140, v[164:167], s[22:23] offset:512
	global_store_dwordx4 v140, v[168:171], s[22:23] offset:528
	s_addk_i32 s2, 0x400
	s_cmpk_ge_u32 s2, 0x420
	s_cselect_b64 vcc, -1, 0
	s_cbranch_vccnz .LBB0_1475
	v_and_b32_e32 v4, 63, v136
	v_ashrrev_i32_e32 v0, 5, v136
	v_readlane_b32 s4, v253, 3
	v_and_b32_e32 v5, -2, v0
	v_lshlrev_b32_e32 v0, 4, v4
	v_mov_b32_e32 v1, 0
	v_readlane_b32 s5, v253, 4
	s_mov_b64 s[0:1], 0x5000
	v_xor_b32_e32 v6, 32, v137
	v_lshl_add_u64 v[2:3], s[4:5], 0, v[0:1]
	v_lshl_add_u64 v[16:17], v[2:3], 0, s[0:1]
	v_and_b32_e32 v3, 64, v137
	v_add_u32_e32 v3, 64, v3
	v_cmp_lt_i32_e64 s[0:1], v6, v3
	v_readlane_b32 s6, v253, 5
	v_readlane_b32 s7, v253, 6
	v_cndmask_b32_e64 v6, v137, v6, s[0:1]
	v_lshlrev_b32_e32 v29, 2, v6
	v_xor_b32_e32 v6, 16, v137
	v_cmp_lt_i32_e64 s[0:1], v6, v3
	v_readlane_b32 s8, v253, 7
	v_readlane_b32 s9, v253, 8
	v_cndmask_b32_e64 v6, v137, v6, s[0:1]
	v_lshlrev_b32_e32 v50, 2, v6
	v_xor_b32_e32 v6, 8, v137
	v_cmp_lt_i32_e64 s[0:1], v6, v3
	v_readlane_b32 s10, v253, 9
	v_readlane_b32 s11, v253, 10
	v_cndmask_b32_e64 v6, v137, v6, s[0:1]
	v_lshlrev_b32_e32 v51, 2, v6
	v_xor_b32_e32 v6, 4, v137
	v_cmp_lt_i32_e64 s[0:1], v6, v3
	v_readlane_b32 s12, v253, 11
	v_readlane_b32 s13, v253, 12
	v_cndmask_b32_e64 v6, v137, v6, s[0:1]
	v_lshlrev_b32_e32 v52, 2, v6
	v_xor_b32_e32 v6, 2, v137
	v_cmp_lt_i32_e64 s[0:1], v6, v3
	v_readlane_b32 s14, v253, 13
	v_readlane_b32 s15, v253, 14
	v_cndmask_b32_e64 v6, v137, v6, s[0:1]
	v_lshlrev_b32_e32 v53, 2, v6
	v_xor_b32_e32 v6, 1, v137
	v_cmp_lt_i32_e64 s[0:1], v6, v3
	v_readlane_b32 s16, v253, 15
	v_readlane_b32 s17, v253, 16
	v_readlane_b32 s18, v253, 17
	v_readlane_b32 s19, v253, 18
	v_mul_u32_u24_e32 v2, 0x4200, v4
	v_cndmask_b32_e64 v3, v137, v6, s[0:1]
	v_lshlrev_b32_e32 v54, 2, v3
	v_lshlrev_b32_e32 v2, 2, v2
	v_mov_b32_e32 v3, v1
	v_readlane_b32 s4, v254, 52
	v_lshl_add_u64 v[18:19], s[44:45], 0, v[2:3]
	v_lshlrev_b32_e32 v2, 3, v4
	v_readlane_b32 s5, v254, 53
	v_cmp_gt_u32_e32 vcc, 16, v4
	v_lshl_add_u64 v[20:21], s[64:65], 0, v[2:3]
	v_lshl_add_u64 v[22:23], s[58:59], 0, v[2:3]
	v_lshl_add_u64 v[24:25], s[4:5], 0, v[0:1]
	v_lshl_add_u32 v26, s2, 4, v5
	s_lshl_b32 s3, s38, 4
	s_mov_b32 s4, 0x3a800000
	s_mov_b32 s5, 0x800000
	v_mov_b32_e32 v28, 0x358637bd
	v_readlane_b32 s6, v254, 54
	v_readlane_b32 s7, v254, 55
	v_readlane_b32 s8, v254, 56
	v_readlane_b32 s9, v254, 57
	v_readlane_b32 s10, v254, 58
	v_readlane_b32 s11, v254, 59
	v_readlane_b32 s12, v254, 60
	v_readlane_b32 s13, v254, 61
	v_readlane_b32 s14, v254, 62
	v_readlane_b32 s15, v254, 63
	v_readlane_b32 s16, v255, 0
	v_readlane_b32 s17, v255, 1
	v_readlane_b32 s18, v255, 2
	v_readlane_b32 s19, v255, 3
	s_branch .LBB0_1471
